# RWKV scan consumer: q sums of two tokens reduced together (one 4-value transpose-reduce over the 16 lanes: 12 ops per token pair instead of 14)
# speedup vs baseline: 1.0030x; 1.0030x over previous
.LBB0_1746:
	s_and_b64 vcc, exec, s[6:7]
	s_cbranch_vccz .LBB0_1797
	v_readlane_b32 s4, v254, 37
	v_readlane_b32 s7, v254, 40
	s_cmp_lt_u32 s7, 2
	v_readlane_b32 s5, v254, 38
	v_readlane_b32 s6, v254, 39
	s_cbranch_scc0 .LBB0_1797
	s_ashr_i32 s18, s28, 5
	s_movk_i32 s0, 0x100
	s_waitcnt vmcnt(0)
	v_and_b32_e32 v4, 63, v34
	v_lshrrev_b32_e32 v23, 6, v34
	s_and_b32 s27, s28, 1
	s_bfe_u32 s26, s28, 0x40001
	s_ashr_i32 s19, s18, 31
	v_cmp_gt_u32_e32 vcc, s0, v34
	s_and_saveexec_b64 s[0:1], vcc
	s_xor_b64 s[20:21], exec, s[0:1]
	s_cbranch_execz .LBB0_1752
	v_lshrrev_b32_e32 v1, 4, v4
	v_lshlrev_b32_e32 v1, 1, v1
	v_lshl_or_b32 v1, v23, 3, v1
	v_and_b32_e32 v2, 3, v4
	v_bfe_u32 v13, v4, 3, 1
	v_bfe_u32 v3, v4, 2, 1
	v_and_b32_e32 v10, 15, v4
	s_waitcnt lgkmcnt(0)
	s_barrier
	v_add_u32_e32 v3, v1, v3
	v_lshlrev_b32_e32 v3, 2, v3
	v_lshl_or_b32 v12, v2, 1, v13
	v_lshlrev_b32_e32 v12, 7, v12
	s_add_i32 s0, 0, 0x18000
	v_lshlrev_b32_e32 v10, 4, v10
	v_cmp_eq_u32_e32 vcc, 7, v2
	v_add3_u32 v11, s0, v12, v3
	v_cmp_eq_u32_e64 s[0:1], 0, v2
	v_cmp_eq_u32_e64 s[6:7], 1, v2
	v_cmp_eq_u32_e64 s[8:9], 2, v2
	v_cmp_eq_u32_e64 s[10:11], 3, v2
	v_cmp_eq_u32_e64 s[12:13], 4, v2
	v_cmp_eq_u32_e64 s[14:15], 5, v2
	v_cmp_eq_u32_e64 s[16:17], 6, v2
	v_mov_b32_e32 v2, 0
	s_lshl_b32 s5, s27, 7
	s_mov_b32 s22, 0
	v_mov_b32_e32 v3, v2
	v_mov_b32_e32 v4, v2
	v_mov_b32_e32 v5, v2
	v_mov_b32_e32 v6, v2
	v_mov_b32_e32 v7, v2
	v_mov_b32_e32 v8, v2
	v_mov_b32_e32 v9, v2
	s_setprio 3
.LBB0_1750:
	s_and_b32 s23, s22, 1
	s_mul_i32 s2, s23, 0xc000
	s_add_i32 s2, s2, 0
	v_add_u32_e32 v20, s2, v10
	s_add_i32 s2, s2, s5
	v_lshl_add_u32 v21, v1, 2, s2
	ds_read_b128 v[36:39], v20 offset:0
	ds_read_b128 v[40:43], v20 offset:8192
	ds_read_b64 v[56:57], v21 offset:40960
	ds_read_b128 v[48:51], v20 offset:24576
	ds_read_b128 v[44:47], v20 offset:16384
	ds_read_b128 v[52:55], v20 offset:32768
	s_waitcnt lgkmcnt(0)
	v_pk_mul_f32 v[22:23], v[2:3], v[36:37] op_sel:[0,0] op_sel_hi:[1,0]
	ds_read_b128 v[60:63], v20 offset:256
	v_pk_fma_f32 v[22:23], v[4:5], v[36:37], v[22:23] op_sel:[0,1,0] op_sel_hi:[1,1,1]
	ds_read_b128 v[64:67], v20 offset:8448
	v_pk_fma_f32 v[22:23], v[6:7], v[38:39], v[22:23] op_sel:[0,0,0] op_sel_hi:[1,0,1]
	ds_read_b64 v[80:81], v21 offset:41216
	v_pk_fma_f32 v[22:23], v[8:9], v[38:39], v[22:23] op_sel:[0,1,0] op_sel_hi:[1,1,1]
	ds_read_b128 v[72:75], v20 offset:24832
	ds_read_b128 v[68:71], v20 offset:16640
	ds_read_b128 v[76:79], v20 offset:33024
	v_add_f32_dpp v22, v22, v22 quad_perm:[1,0,3,2] row_mask:0xf bank_mask:0xf
	v_add_f32_dpp v23, v23, v23 quad_perm:[1,0,3,2] row_mask:0xf bank_mask:0xf
	v_pk_mul_f32 v[84:85], v[2:3], v[40:41] op_sel:[0,0] op_sel_hi:[1,0]
	v_pk_mul_f32 v[86:87], v[4:5], v[40:41] op_sel:[0,1] op_sel_hi:[1,1]
	v_add_f32_dpp v22, v22, v22 quad_perm:[2,3,0,1] row_mask:0xf bank_mask:0xf
	v_add_f32_dpp v23, v23, v23 quad_perm:[2,3,0,1] row_mask:0xf bank_mask:0xf
	v_pk_mul_f32 v[88:89], v[6:7], v[42:43] op_sel:[0,0] op_sel_hi:[1,0]
	v_pk_mul_f32 v[90:91], v[8:9], v[42:43] op_sel:[0,1] op_sel_hi:[1,1]
	v_add_f32_dpp v22, v22, v22 row_half_mirror row_mask:0xf bank_mask:0xf
	v_add_f32_dpp v23, v23, v23 row_half_mirror row_mask:0xf bank_mask:0xf
	v_pk_fma_f32 v[84:85], v[48:49], v[56:57], v[84:85] op_sel:[0,0,0] op_sel_hi:[0,1,1]
	v_pk_fma_f32 v[86:87], v[48:49], v[56:57], v[86:87] op_sel:[1,0,0] op_sel_hi:[1,1,1]
	v_add_f32_dpp v22, v22, v22 row_mirror row_mask:0xf bank_mask:0xf
	v_add_f32_dpp v23, v23, v23 row_mirror row_mask:0xf bank_mask:0xf
	v_pk_fma_f32 v[88:89], v[50:51], v[56:57], v[88:89] op_sel:[0,0,0] op_sel_hi:[0,1,1]
	v_pk_fma_f32 v[90:91], v[50:51], v[56:57], v[90:91] op_sel:[1,0,0] op_sel_hi:[1,1,1]
	v_pk_fma_f32 v[2:3], v[44:45], v[22:23], v[84:85] op_sel:[0,0,0] op_sel_hi:[0,1,1] neg_lo:[1,0,0] neg_hi:[1,0,0]
	v_pk_fma_f32 v[4:5], v[44:45], v[22:23], v[86:87] op_sel:[1,0,0] op_sel_hi:[1,1,1] neg_lo:[1,0,0] neg_hi:[1,0,0]
	v_pk_fma_f32 v[6:7], v[46:47], v[22:23], v[88:89] op_sel:[0,0,0] op_sel_hi:[0,1,1] neg_lo:[1,0,0] neg_hi:[1,0,0]
	v_pk_fma_f32 v[8:9], v[46:47], v[22:23], v[90:91] op_sel:[1,0,0] op_sel_hi:[1,1,1] neg_lo:[1,0,0] neg_hi:[1,0,0]
	s_waitcnt lgkmcnt(0)
	v_pk_mul_f32 v[22:23], v[2:3], v[60:61] op_sel:[0,0] op_sel_hi:[1,0]
	v_pk_mul_f32 v[24:25], v[2:3], v[52:53] op_sel:[0,0] op_sel_hi:[1,0]
	ds_read_b128 v[36:39], v20 offset:512
	v_pk_fma_f32 v[22:23], v[4:5], v[60:61], v[22:23] op_sel:[0,1,0] op_sel_hi:[1,1,1]
	v_pk_mul_f32 v[84:85], v[4:5], v[52:53] op_sel:[0,1] op_sel_hi:[1,1]
	ds_read_b128 v[40:43], v20 offset:8704
	v_pk_fma_f32 v[22:23], v[6:7], v[62:63], v[22:23] op_sel:[0,0,0] op_sel_hi:[1,0,1]
	v_pk_fma_f32 v[24:25], v[6:7], v[54:55], v[24:25] op_sel:[0,0,0] op_sel_hi:[1,0,1]
	ds_read_b64 v[56:57], v21 offset:41472
	v_pk_fma_f32 v[22:23], v[8:9], v[62:63], v[22:23] op_sel:[0,1,0] op_sel_hi:[1,1,1]
	v_pk_fma_f32 v[84:85], v[8:9], v[54:55], v[84:85] op_sel:[0,1,0] op_sel_hi:[1,1,1]
	ds_read_b128 v[48:51], v20 offset:25088
	v_pk_add_f32 v[24:25], v[24:25], v[84:85]
	ds_read_b128 v[44:47], v20 offset:16896
	ds_read_b128 v[52:55], v20 offset:33280
	v_add_f32_dpp v22, v22, v22 quad_perm:[1,0,3,2] row_mask:0xf bank_mask:0xf
	v_add_f32_dpp v23, v23, v23 quad_perm:[1,0,3,2] row_mask:0xf bank_mask:0xf
	v_pk_mul_f32 v[84:85], v[2:3], v[64:65] op_sel:[0,0] op_sel_hi:[1,0]
	v_pk_mul_f32 v[86:87], v[4:5], v[64:65] op_sel:[0,1] op_sel_hi:[1,1]
	v_add_f32_dpp v22, v22, v22 quad_perm:[2,3,0,1] row_mask:0xf bank_mask:0xf
	v_add_f32_dpp v23, v23, v23 quad_perm:[2,3,0,1] row_mask:0xf bank_mask:0xf
	v_pk_mul_f32 v[88:89], v[6:7], v[66:67] op_sel:[0,0] op_sel_hi:[1,0]
	v_pk_mul_f32 v[90:91], v[8:9], v[66:67] op_sel:[0,1] op_sel_hi:[1,1]
	v_add_f32_dpp v22, v22, v22 row_half_mirror row_mask:0xf bank_mask:0xf
	v_add_f32_dpp v23, v23, v23 row_half_mirror row_mask:0xf bank_mask:0xf
	v_pk_fma_f32 v[84:85], v[72:73], v[80:81], v[84:85] op_sel:[0,0,0] op_sel_hi:[0,1,1]
	v_pk_fma_f32 v[86:87], v[72:73], v[80:81], v[86:87] op_sel:[1,0,0] op_sel_hi:[1,1,1]
	v_add_f32_dpp v22, v22, v22 row_mirror row_mask:0xf bank_mask:0xf
	v_add_f32_dpp v23, v23, v23 row_mirror row_mask:0xf bank_mask:0xf
	v_pk_fma_f32 v[88:89], v[74:75], v[80:81], v[88:89] op_sel:[0,0,0] op_sel_hi:[0,1,1]
	v_pk_fma_f32 v[90:91], v[74:75], v[80:81], v[90:91] op_sel:[1,0,0] op_sel_hi:[1,1,1]
	v_pk_fma_f32 v[2:3], v[68:69], v[22:23], v[84:85] op_sel:[0,0,0] op_sel_hi:[0,1,1] neg_lo:[1,0,0] neg_hi:[1,0,0]
	v_pk_fma_f32 v[4:5], v[68:69], v[22:23], v[86:87] op_sel:[1,0,0] op_sel_hi:[1,1,1] neg_lo:[1,0,0] neg_hi:[1,0,0]
	v_pk_fma_f32 v[6:7], v[70:71], v[22:23], v[88:89] op_sel:[0,0,0] op_sel_hi:[0,1,1] neg_lo:[1,0,0] neg_hi:[1,0,0]
	v_pk_fma_f32 v[8:9], v[70:71], v[22:23], v[90:91] op_sel:[1,0,0] op_sel_hi:[1,1,1] neg_lo:[1,0,0] neg_hi:[1,0,0]
	s_waitcnt lgkmcnt(0)
	v_pk_mul_f32 v[22:23], v[2:3], v[36:37] op_sel:[0,0] op_sel_hi:[1,0]
	v_pk_mul_f32 v[26:27], v[2:3], v[76:77] op_sel:[0,0] op_sel_hi:[1,0]
	ds_read_b128 v[60:63], v20 offset:768
	v_pk_fma_f32 v[22:23], v[4:5], v[36:37], v[22:23] op_sel:[0,1,0] op_sel_hi:[1,1,1]
	v_pk_mul_f32 v[84:85], v[4:5], v[76:77] op_sel:[0,1] op_sel_hi:[1,1]
	ds_read_b128 v[64:67], v20 offset:8960
	v_pk_fma_f32 v[22:23], v[6:7], v[38:39], v[22:23] op_sel:[0,0,0] op_sel_hi:[1,0,1]
	v_pk_fma_f32 v[26:27], v[6:7], v[78:79], v[26:27] op_sel:[0,0,0] op_sel_hi:[1,0,1]
	ds_read_b64 v[80:81], v21 offset:41728
	v_pk_fma_f32 v[22:23], v[8:9], v[38:39], v[22:23] op_sel:[0,1,0] op_sel_hi:[1,1,1]
	v_pk_fma_f32 v[84:85], v[8:9], v[78:79], v[84:85] op_sel:[0,1,0] op_sel_hi:[1,1,1]
	ds_read_b128 v[72:75], v20 offset:25344
	v_pk_add_f32 v[26:27], v[26:27], v[84:85]
	ds_read_b128 v[68:71], v20 offset:17152
	ds_read_b128 v[76:79], v20 offset:33536
	v_add_f32_dpp v22, v22, v22 quad_perm:[1,0,3,2] row_mask:0xf bank_mask:0xf
	v_add_f32_dpp v23, v23, v23 quad_perm:[1,0,3,2] row_mask:0xf bank_mask:0xf
	v_pk_mul_f32 v[84:85], v[2:3], v[40:41] op_sel:[0,0] op_sel_hi:[1,0]
	v_pk_mul_f32 v[86:87], v[4:5], v[40:41] op_sel:[0,1] op_sel_hi:[1,1]
	v_add_f32_dpp v22, v22, v22 quad_perm:[2,3,0,1] row_mask:0xf bank_mask:0xf
	v_add_f32_dpp v23, v23, v23 quad_perm:[2,3,0,1] row_mask:0xf bank_mask:0xf
	v_pk_mul_f32 v[88:89], v[6:7], v[42:43] op_sel:[0,0] op_sel_hi:[1,0]
	v_pk_mul_f32 v[90:91], v[8:9], v[42:43] op_sel:[0,1] op_sel_hi:[1,1]
	v_add_f32_dpp v22, v22, v22 row_half_mirror row_mask:0xf bank_mask:0xf
	v_add_f32_dpp v23, v23, v23 row_half_mirror row_mask:0xf bank_mask:0xf
	v_pk_fma_f32 v[84:85], v[48:49], v[56:57], v[84:85] op_sel:[0,0,0] op_sel_hi:[0,1,1]
	v_pk_fma_f32 v[86:87], v[48:49], v[56:57], v[86:87] op_sel:[1,0,0] op_sel_hi:[1,1,1]
	v_add_f32_dpp v22, v22, v22 row_mirror row_mask:0xf bank_mask:0xf
	v_add_f32_dpp v23, v23, v23 row_mirror row_mask:0xf bank_mask:0xf
	v_pk_fma_f32 v[88:89], v[50:51], v[56:57], v[88:89] op_sel:[0,0,0] op_sel_hi:[0,1,1]
	v_pk_fma_f32 v[90:91], v[50:51], v[56:57], v[90:91] op_sel:[1,0,0] op_sel_hi:[1,1,1]
	v_pk_fma_f32 v[2:3], v[44:45], v[22:23], v[84:85] op_sel:[0,0,0] op_sel_hi:[0,1,1] neg_lo:[1,0,0] neg_hi:[1,0,0]
	v_pk_fma_f32 v[4:5], v[44:45], v[22:23], v[86:87] op_sel:[1,0,0] op_sel_hi:[1,1,1] neg_lo:[1,0,0] neg_hi:[1,0,0]
	v_pk_fma_f32 v[6:7], v[46:47], v[22:23], v[88:89] op_sel:[0,0,0] op_sel_hi:[0,1,1] neg_lo:[1,0,0] neg_hi:[1,0,0]
	v_pk_fma_f32 v[8:9], v[46:47], v[22:23], v[90:91] op_sel:[1,0,0] op_sel_hi:[1,1,1] neg_lo:[1,0,0] neg_hi:[1,0,0]
	s_waitcnt lgkmcnt(0)
	v_pk_mul_f32 v[22:23], v[2:3], v[60:61] op_sel:[0,0] op_sel_hi:[1,0]
	v_pk_mul_f32 v[28:29], v[2:3], v[52:53] op_sel:[0,0] op_sel_hi:[1,0]
	ds_read_b128 v[36:39], v20 offset:1024
	v_pk_fma_f32 v[22:23], v[4:5], v[60:61], v[22:23] op_sel:[0,1,0] op_sel_hi:[1,1,1]
	v_pk_mul_f32 v[84:85], v[4:5], v[52:53] op_sel:[0,1] op_sel_hi:[1,1]
	ds_read_b128 v[40:43], v20 offset:9216
	v_pk_fma_f32 v[22:23], v[6:7], v[62:63], v[22:23] op_sel:[0,0,0] op_sel_hi:[1,0,1]
	v_pk_fma_f32 v[28:29], v[6:7], v[54:55], v[28:29] op_sel:[0,0,0] op_sel_hi:[1,0,1]
	ds_read_b64 v[56:57], v21 offset:41984
	v_pk_fma_f32 v[22:23], v[8:9], v[62:63], v[22:23] op_sel:[0,1,0] op_sel_hi:[1,1,1]
	v_pk_fma_f32 v[84:85], v[8:9], v[54:55], v[84:85] op_sel:[0,1,0] op_sel_hi:[1,1,1]
	ds_read_b128 v[48:51], v20 offset:25600
	v_pk_add_f32 v[28:29], v[28:29], v[84:85]
	ds_read_b128 v[44:47], v20 offset:17408
	ds_read_b128 v[52:55], v20 offset:33792
	v_add_f32_dpp v24, v24, v24 row_ror:12 row_mask:0xf bank_mask:0x5
	v_add_f32_dpp v25, v25, v25 row_ror:4 row_mask:0xf bank_mask:0xa
	v_add_f32_dpp v22, v22, v22 quad_perm:[1,0,3,2] row_mask:0xf bank_mask:0xf
	v_add_f32_dpp v23, v23, v23 quad_perm:[1,0,3,2] row_mask:0xf bank_mask:0xf
	v_pk_mul_f32 v[84:85], v[2:3], v[64:65] op_sel:[0,0] op_sel_hi:[1,0]
	v_pk_mul_f32 v[86:87], v[4:5], v[64:65] op_sel:[0,1] op_sel_hi:[1,1]
	v_add_f32_dpp v26, v26, v26 row_ror:12 row_mask:0xf bank_mask:0x5
	v_add_f32_dpp v22, v22, v22 quad_perm:[2,3,0,1] row_mask:0xf bank_mask:0xf
	v_add_f32_dpp v23, v23, v23 quad_perm:[2,3,0,1] row_mask:0xf bank_mask:0xf
	v_pk_mul_f32 v[88:89], v[6:7], v[66:67] op_sel:[0,0] op_sel_hi:[1,0]
	v_pk_mul_f32 v[90:91], v[8:9], v[66:67] op_sel:[0,1] op_sel_hi:[1,1]
	v_add_f32_dpp v27, v27, v27 row_ror:4 row_mask:0xf bank_mask:0xa
	v_add_f32_dpp v22, v22, v22 row_half_mirror row_mask:0xf bank_mask:0xf
	v_add_f32_dpp v23, v23, v23 row_half_mirror row_mask:0xf bank_mask:0xf
	v_pk_fma_f32 v[84:85], v[72:73], v[80:81], v[84:85] op_sel:[0,0,0] op_sel_hi:[0,1,1]
	v_pk_fma_f32 v[86:87], v[72:73], v[80:81], v[86:87] op_sel:[1,0,0] op_sel_hi:[1,1,1]
	v_mov_b32_dpp v24, v25 quad_perm:[0,1,2,3] row_mask:0xf bank_mask:0xa
	v_add_f32_dpp v22, v22, v22 row_mirror row_mask:0xf bank_mask:0xf
	v_add_f32_dpp v23, v23, v23 row_mirror row_mask:0xf bank_mask:0xf
	v_pk_fma_f32 v[88:89], v[74:75], v[80:81], v[88:89] op_sel:[0,0,0] op_sel_hi:[0,1,1]
	v_pk_fma_f32 v[90:91], v[74:75], v[80:81], v[90:91] op_sel:[1,0,0] op_sel_hi:[1,1,1]
	v_mov_b32_dpp v26, v27 quad_perm:[0,1,2,3] row_mask:0xf bank_mask:0xa
	v_pk_fma_f32 v[2:3], v[68:69], v[22:23], v[84:85] op_sel:[0,0,0] op_sel_hi:[0,1,1] neg_lo:[1,0,0] neg_hi:[1,0,0]
	v_pk_fma_f32 v[4:5], v[68:69], v[22:23], v[86:87] op_sel:[1,0,0] op_sel_hi:[1,1,1] neg_lo:[1,0,0] neg_hi:[1,0,0]
	v_pk_fma_f32 v[6:7], v[70:71], v[22:23], v[88:89] op_sel:[0,0,0] op_sel_hi:[0,1,1] neg_lo:[1,0,0] neg_hi:[1,0,0]
	v_pk_fma_f32 v[8:9], v[70:71], v[22:23], v[90:91] op_sel:[1,0,0] op_sel_hi:[1,1,1] neg_lo:[1,0,0] neg_hi:[1,0,0]
	s_waitcnt lgkmcnt(0)
	v_pk_mul_f32 v[22:23], v[2:3], v[36:37] op_sel:[0,0] op_sel_hi:[1,0]
	v_pk_mul_f32 v[58:59], v[2:3], v[76:77] op_sel:[0,0] op_sel_hi:[1,0]
	ds_read_b128 v[60:63], v20 offset:1280
	v_pk_fma_f32 v[22:23], v[4:5], v[36:37], v[22:23] op_sel:[0,1,0] op_sel_hi:[1,1,1]
	v_pk_mul_f32 v[84:85], v[4:5], v[76:77] op_sel:[0,1] op_sel_hi:[1,1]
	ds_read_b128 v[64:67], v20 offset:9472
	v_pk_fma_f32 v[22:23], v[6:7], v[38:39], v[22:23] op_sel:[0,0,0] op_sel_hi:[1,0,1]
	v_pk_fma_f32 v[58:59], v[6:7], v[78:79], v[58:59] op_sel:[0,0,0] op_sel_hi:[1,0,1]
	ds_read_b64 v[80:81], v21 offset:42240
	v_pk_fma_f32 v[22:23], v[8:9], v[38:39], v[22:23] op_sel:[0,1,0] op_sel_hi:[1,1,1]
	v_pk_fma_f32 v[84:85], v[8:9], v[78:79], v[84:85] op_sel:[0,1,0] op_sel_hi:[1,1,1]
	ds_read_b128 v[72:75], v20 offset:25856
	v_pk_add_f32 v[58:59], v[58:59], v[84:85]
	ds_read_b128 v[68:71], v20 offset:17664
	ds_read_b128 v[76:79], v20 offset:34048
	v_add_f32_dpp v24, v24, v24 row_ror:8 row_mask:0xf bank_mask:0x3
	v_add_f32_dpp v26, v26, v26 row_ror:8 row_mask:0xf bank_mask:0xc
	v_add_f32_dpp v22, v22, v22 quad_perm:[1,0,3,2] row_mask:0xf bank_mask:0xf
	v_add_f32_dpp v23, v23, v23 quad_perm:[1,0,3,2] row_mask:0xf bank_mask:0xf
	v_pk_mul_f32 v[84:85], v[2:3], v[40:41] op_sel:[0,0] op_sel_hi:[1,0]
	v_pk_mul_f32 v[86:87], v[4:5], v[40:41] op_sel:[0,1] op_sel_hi:[1,1]
	v_mov_b32_dpp v24, v26 quad_perm:[0,1,2,3] row_mask:0xf bank_mask:0xc
	v_add_f32_dpp v22, v22, v22 quad_perm:[2,3,0,1] row_mask:0xf bank_mask:0xf
	v_add_f32_dpp v23, v23, v23 quad_perm:[2,3,0,1] row_mask:0xf bank_mask:0xf
	v_pk_mul_f32 v[88:89], v[6:7], v[42:43] op_sel:[0,0] op_sel_hi:[1,0]
	v_pk_mul_f32 v[90:91], v[8:9], v[42:43] op_sel:[0,1] op_sel_hi:[1,1]
	v_add_f32_dpp v24, v24, v24 quad_perm:[1,0,3,2] row_mask:0xf bank_mask:0xf
	v_add_f32_dpp v22, v22, v22 row_half_mirror row_mask:0xf bank_mask:0xf
	v_add_f32_dpp v23, v23, v23 row_half_mirror row_mask:0xf bank_mask:0xf
	v_pk_fma_f32 v[84:85], v[48:49], v[56:57], v[84:85] op_sel:[0,0,0] op_sel_hi:[0,1,1]
	v_pk_fma_f32 v[86:87], v[48:49], v[56:57], v[86:87] op_sel:[1,0,0] op_sel_hi:[1,1,1]
	v_add_f32_dpp v24, v24, v24 quad_perm:[2,3,0,1] row_mask:0xf bank_mask:0xf
	v_add_f32_dpp v22, v22, v22 row_mirror row_mask:0xf bank_mask:0xf
	v_add_f32_dpp v23, v23, v23 row_mirror row_mask:0xf bank_mask:0xf
	v_pk_fma_f32 v[88:89], v[50:51], v[56:57], v[88:89] op_sel:[0,0,0] op_sel_hi:[0,1,1]
	v_pk_fma_f32 v[90:91], v[50:51], v[56:57], v[90:91] op_sel:[1,0,0] op_sel_hi:[1,1,1]
	v_cndmask_b32_e64 v30, 0, v24, s[0:1]
	v_pk_fma_f32 v[2:3], v[44:45], v[22:23], v[84:85] op_sel:[0,0,0] op_sel_hi:[0,1,1] neg_lo:[1,0,0] neg_hi:[1,0,0]
	v_pk_fma_f32 v[4:5], v[44:45], v[22:23], v[86:87] op_sel:[1,0,0] op_sel_hi:[1,1,1] neg_lo:[1,0,0] neg_hi:[1,0,0]
	v_pk_fma_f32 v[6:7], v[46:47], v[22:23], v[88:89] op_sel:[0,0,0] op_sel_hi:[0,1,1] neg_lo:[1,0,0] neg_hi:[1,0,0]
	v_pk_fma_f32 v[8:9], v[46:47], v[22:23], v[90:91] op_sel:[1,0,0] op_sel_hi:[1,1,1] neg_lo:[1,0,0] neg_hi:[1,0,0]
	s_waitcnt lgkmcnt(0)
	v_pk_mul_f32 v[22:23], v[2:3], v[60:61] op_sel:[0,0] op_sel_hi:[1,0]
	v_pk_mul_f32 v[24:25], v[2:3], v[52:53] op_sel:[0,0] op_sel_hi:[1,0]
	ds_read_b128 v[36:39], v20 offset:1536
	v_pk_fma_f32 v[22:23], v[4:5], v[60:61], v[22:23] op_sel:[0,1,0] op_sel_hi:[1,1,1]
	v_pk_mul_f32 v[84:85], v[4:5], v[52:53] op_sel:[0,1] op_sel_hi:[1,1]
	ds_read_b128 v[40:43], v20 offset:9728
	v_pk_fma_f32 v[22:23], v[6:7], v[62:63], v[22:23] op_sel:[0,0,0] op_sel_hi:[1,0,1]
	v_pk_fma_f32 v[24:25], v[6:7], v[54:55], v[24:25] op_sel:[0,0,0] op_sel_hi:[1,0,1]
	ds_read_b64 v[56:57], v21 offset:42496
	v_pk_fma_f32 v[22:23], v[8:9], v[62:63], v[22:23] op_sel:[0,1,0] op_sel_hi:[1,1,1]
	v_pk_fma_f32 v[84:85], v[8:9], v[54:55], v[84:85] op_sel:[0,1,0] op_sel_hi:[1,1,1]
	ds_read_b128 v[48:51], v20 offset:26112
	v_pk_add_f32 v[24:25], v[24:25], v[84:85]
	ds_read_b128 v[44:47], v20 offset:17920
	ds_read_b128 v[52:55], v20 offset:34304
	v_add_f32_dpp v28, v28, v28 row_ror:12 row_mask:0xf bank_mask:0x5
	v_add_f32_dpp v29, v29, v29 row_ror:4 row_mask:0xf bank_mask:0xa
	v_add_f32_dpp v22, v22, v22 quad_perm:[1,0,3,2] row_mask:0xf bank_mask:0xf
	v_add_f32_dpp v23, v23, v23 quad_perm:[1,0,3,2] row_mask:0xf bank_mask:0xf
	v_pk_mul_f32 v[84:85], v[2:3], v[64:65] op_sel:[0,0] op_sel_hi:[1,0]
	v_pk_mul_f32 v[86:87], v[4:5], v[64:65] op_sel:[0,1] op_sel_hi:[1,1]
	v_add_f32_dpp v58, v58, v58 row_ror:12 row_mask:0xf bank_mask:0x5
	v_add_f32_dpp v22, v22, v22 quad_perm:[2,3,0,1] row_mask:0xf bank_mask:0xf
	v_add_f32_dpp v23, v23, v23 quad_perm:[2,3,0,1] row_mask:0xf bank_mask:0xf
	v_pk_mul_f32 v[88:89], v[6:7], v[66:67] op_sel:[0,0] op_sel_hi:[1,0]
	v_pk_mul_f32 v[90:91], v[8:9], v[66:67] op_sel:[0,1] op_sel_hi:[1,1]
	v_add_f32_dpp v59, v59, v59 row_ror:4 row_mask:0xf bank_mask:0xa
	v_add_f32_dpp v22, v22, v22 row_half_mirror row_mask:0xf bank_mask:0xf
	v_add_f32_dpp v23, v23, v23 row_half_mirror row_mask:0xf bank_mask:0xf
	v_pk_fma_f32 v[84:85], v[72:73], v[80:81], v[84:85] op_sel:[0,0,0] op_sel_hi:[0,1,1]
	v_pk_fma_f32 v[86:87], v[72:73], v[80:81], v[86:87] op_sel:[1,0,0] op_sel_hi:[1,1,1]
	v_mov_b32_dpp v28, v29 quad_perm:[0,1,2,3] row_mask:0xf bank_mask:0xa
	v_add_f32_dpp v22, v22, v22 row_mirror row_mask:0xf bank_mask:0xf
	v_add_f32_dpp v23, v23, v23 row_mirror row_mask:0xf bank_mask:0xf
	v_pk_fma_f32 v[88:89], v[74:75], v[80:81], v[88:89] op_sel:[0,0,0] op_sel_hi:[0,1,1]
	v_pk_fma_f32 v[90:91], v[74:75], v[80:81], v[90:91] op_sel:[1,0,0] op_sel_hi:[1,1,1]
	v_mov_b32_dpp v58, v59 quad_perm:[0,1,2,3] row_mask:0xf bank_mask:0xa
	v_pk_fma_f32 v[2:3], v[68:69], v[22:23], v[84:85] op_sel:[0,0,0] op_sel_hi:[0,1,1] neg_lo:[1,0,0] neg_hi:[1,0,0]
	v_pk_fma_f32 v[4:5], v[68:69], v[22:23], v[86:87] op_sel:[1,0,0] op_sel_hi:[1,1,1] neg_lo:[1,0,0] neg_hi:[1,0,0]
	v_pk_fma_f32 v[6:7], v[70:71], v[22:23], v[88:89] op_sel:[0,0,0] op_sel_hi:[0,1,1] neg_lo:[1,0,0] neg_hi:[1,0,0]
	v_pk_fma_f32 v[8:9], v[70:71], v[22:23], v[90:91] op_sel:[1,0,0] op_sel_hi:[1,1,1] neg_lo:[1,0,0] neg_hi:[1,0,0]
	s_waitcnt lgkmcnt(0)
	v_pk_mul_f32 v[22:23], v[2:3], v[36:37] op_sel:[0,0] op_sel_hi:[1,0]
	v_pk_mul_f32 v[26:27], v[2:3], v[76:77] op_sel:[0,0] op_sel_hi:[1,0]
	ds_read_b128 v[60:63], v20 offset:1792
	v_pk_fma_f32 v[22:23], v[4:5], v[36:37], v[22:23] op_sel:[0,1,0] op_sel_hi:[1,1,1]
	v_pk_mul_f32 v[84:85], v[4:5], v[76:77] op_sel:[0,1] op_sel_hi:[1,1]
	ds_read_b128 v[64:67], v20 offset:9984
	v_pk_fma_f32 v[22:23], v[6:7], v[38:39], v[22:23] op_sel:[0,0,0] op_sel_hi:[1,0,1]
	v_pk_fma_f32 v[26:27], v[6:7], v[78:79], v[26:27] op_sel:[0,0,0] op_sel_hi:[1,0,1]
	ds_read_b64 v[80:81], v21 offset:42752
	v_pk_fma_f32 v[22:23], v[8:9], v[38:39], v[22:23] op_sel:[0,1,0] op_sel_hi:[1,1,1]
	v_pk_fma_f32 v[84:85], v[8:9], v[78:79], v[84:85] op_sel:[0,1,0] op_sel_hi:[1,1,1]
	ds_read_b128 v[72:75], v20 offset:26368
	v_pk_add_f32 v[26:27], v[26:27], v[84:85]
	ds_read_b128 v[68:71], v20 offset:18176
	ds_read_b128 v[76:79], v20 offset:34560
	v_add_f32_dpp v28, v28, v28 row_ror:8 row_mask:0xf bank_mask:0x3
	v_add_f32_dpp v58, v58, v58 row_ror:8 row_mask:0xf bank_mask:0xc
	v_add_f32_dpp v22, v22, v22 quad_perm:[1,0,3,2] row_mask:0xf bank_mask:0xf
	v_add_f32_dpp v23, v23, v23 quad_perm:[1,0,3,2] row_mask:0xf bank_mask:0xf
	v_pk_mul_f32 v[84:85], v[2:3], v[40:41] op_sel:[0,0] op_sel_hi:[1,0]
	v_pk_mul_f32 v[86:87], v[4:5], v[40:41] op_sel:[0,1] op_sel_hi:[1,1]
	v_mov_b32_dpp v28, v58 quad_perm:[0,1,2,3] row_mask:0xf bank_mask:0xc
	v_add_f32_dpp v22, v22, v22 quad_perm:[2,3,0,1] row_mask:0xf bank_mask:0xf
	v_add_f32_dpp v23, v23, v23 quad_perm:[2,3,0,1] row_mask:0xf bank_mask:0xf
	v_pk_mul_f32 v[88:89], v[6:7], v[42:43] op_sel:[0,0] op_sel_hi:[1,0]
	v_pk_mul_f32 v[90:91], v[8:9], v[42:43] op_sel:[0,1] op_sel_hi:[1,1]
	v_add_f32_dpp v28, v28, v28 quad_perm:[1,0,3,2] row_mask:0xf bank_mask:0xf
	v_add_f32_dpp v22, v22, v22 row_half_mirror row_mask:0xf bank_mask:0xf
	v_add_f32_dpp v23, v23, v23 row_half_mirror row_mask:0xf bank_mask:0xf
	v_pk_fma_f32 v[84:85], v[48:49], v[56:57], v[84:85] op_sel:[0,0,0] op_sel_hi:[0,1,1]
	v_pk_fma_f32 v[86:87], v[48:49], v[56:57], v[86:87] op_sel:[1,0,0] op_sel_hi:[1,1,1]
	v_add_f32_dpp v28, v28, v28 quad_perm:[2,3,0,1] row_mask:0xf bank_mask:0xf
	v_add_f32_dpp v22, v22, v22 row_mirror row_mask:0xf bank_mask:0xf
	v_add_f32_dpp v23, v23, v23 row_mirror row_mask:0xf bank_mask:0xf
	v_pk_fma_f32 v[88:89], v[50:51], v[56:57], v[88:89] op_sel:[0,0,0] op_sel_hi:[0,1,1]
	v_pk_fma_f32 v[90:91], v[50:51], v[56:57], v[90:91] op_sel:[1,0,0] op_sel_hi:[1,1,1]
	v_cndmask_b32_e64 v30, v30, v28, s[6:7]
	v_pk_fma_f32 v[2:3], v[44:45], v[22:23], v[84:85] op_sel:[0,0,0] op_sel_hi:[0,1,1] neg_lo:[1,0,0] neg_hi:[1,0,0]
	v_pk_fma_f32 v[4:5], v[44:45], v[22:23], v[86:87] op_sel:[1,0,0] op_sel_hi:[1,1,1] neg_lo:[1,0,0] neg_hi:[1,0,0]
	v_pk_fma_f32 v[6:7], v[46:47], v[22:23], v[88:89] op_sel:[0,0,0] op_sel_hi:[0,1,1] neg_lo:[1,0,0] neg_hi:[1,0,0]
	v_pk_fma_f32 v[8:9], v[46:47], v[22:23], v[90:91] op_sel:[1,0,0] op_sel_hi:[1,1,1] neg_lo:[1,0,0] neg_hi:[1,0,0]
	s_waitcnt lgkmcnt(0)
	v_pk_mul_f32 v[22:23], v[2:3], v[60:61] op_sel:[0,0] op_sel_hi:[1,0]
	v_pk_mul_f32 v[28:29], v[2:3], v[52:53] op_sel:[0,0] op_sel_hi:[1,0]
	ds_read_b128 v[36:39], v20 offset:2048
	v_pk_fma_f32 v[22:23], v[4:5], v[60:61], v[22:23] op_sel:[0,1,0] op_sel_hi:[1,1,1]
	v_pk_mul_f32 v[84:85], v[4:5], v[52:53] op_sel:[0,1] op_sel_hi:[1,1]
	ds_read_b128 v[40:43], v20 offset:10240
	v_pk_fma_f32 v[22:23], v[6:7], v[62:63], v[22:23] op_sel:[0,0,0] op_sel_hi:[1,0,1]
	v_pk_fma_f32 v[28:29], v[6:7], v[54:55], v[28:29] op_sel:[0,0,0] op_sel_hi:[1,0,1]
	ds_read_b64 v[56:57], v21 offset:43008
	v_pk_fma_f32 v[22:23], v[8:9], v[62:63], v[22:23] op_sel:[0,1,0] op_sel_hi:[1,1,1]
	v_pk_fma_f32 v[84:85], v[8:9], v[54:55], v[84:85] op_sel:[0,1,0] op_sel_hi:[1,1,1]
	ds_read_b128 v[48:51], v20 offset:26624
	v_pk_add_f32 v[28:29], v[28:29], v[84:85]
	ds_read_b128 v[44:47], v20 offset:18432
	ds_read_b128 v[52:55], v20 offset:34816
	v_add_f32_dpp v24, v24, v24 row_ror:12 row_mask:0xf bank_mask:0x5
	v_add_f32_dpp v25, v25, v25 row_ror:4 row_mask:0xf bank_mask:0xa
	v_add_f32_dpp v22, v22, v22 quad_perm:[1,0,3,2] row_mask:0xf bank_mask:0xf
	v_add_f32_dpp v23, v23, v23 quad_perm:[1,0,3,2] row_mask:0xf bank_mask:0xf
	v_pk_mul_f32 v[84:85], v[2:3], v[64:65] op_sel:[0,0] op_sel_hi:[1,0]
	v_pk_mul_f32 v[86:87], v[4:5], v[64:65] op_sel:[0,1] op_sel_hi:[1,1]
	v_add_f32_dpp v26, v26, v26 row_ror:12 row_mask:0xf bank_mask:0x5
	v_add_f32_dpp v22, v22, v22 quad_perm:[2,3,0,1] row_mask:0xf bank_mask:0xf
	v_add_f32_dpp v23, v23, v23 quad_perm:[2,3,0,1] row_mask:0xf bank_mask:0xf
	v_pk_mul_f32 v[88:89], v[6:7], v[66:67] op_sel:[0,0] op_sel_hi:[1,0]
	v_pk_mul_f32 v[90:91], v[8:9], v[66:67] op_sel:[0,1] op_sel_hi:[1,1]
	v_add_f32_dpp v27, v27, v27 row_ror:4 row_mask:0xf bank_mask:0xa
	v_add_f32_dpp v22, v22, v22 row_half_mirror row_mask:0xf bank_mask:0xf
	v_add_f32_dpp v23, v23, v23 row_half_mirror row_mask:0xf bank_mask:0xf
	v_pk_fma_f32 v[84:85], v[72:73], v[80:81], v[84:85] op_sel:[0,0,0] op_sel_hi:[0,1,1]
	v_pk_fma_f32 v[86:87], v[72:73], v[80:81], v[86:87] op_sel:[1,0,0] op_sel_hi:[1,1,1]
	v_mov_b32_dpp v24, v25 quad_perm:[0,1,2,3] row_mask:0xf bank_mask:0xa
	v_add_f32_dpp v22, v22, v22 row_mirror row_mask:0xf bank_mask:0xf
	v_add_f32_dpp v23, v23, v23 row_mirror row_mask:0xf bank_mask:0xf
	v_pk_fma_f32 v[88:89], v[74:75], v[80:81], v[88:89] op_sel:[0,0,0] op_sel_hi:[0,1,1]
	v_pk_fma_f32 v[90:91], v[74:75], v[80:81], v[90:91] op_sel:[1,0,0] op_sel_hi:[1,1,1]
	v_mov_b32_dpp v26, v27 quad_perm:[0,1,2,3] row_mask:0xf bank_mask:0xa
	v_pk_fma_f32 v[2:3], v[68:69], v[22:23], v[84:85] op_sel:[0,0,0] op_sel_hi:[0,1,1] neg_lo:[1,0,0] neg_hi:[1,0,0]
	v_pk_fma_f32 v[4:5], v[68:69], v[22:23], v[86:87] op_sel:[1,0,0] op_sel_hi:[1,1,1] neg_lo:[1,0,0] neg_hi:[1,0,0]
	v_pk_fma_f32 v[6:7], v[70:71], v[22:23], v[88:89] op_sel:[0,0,0] op_sel_hi:[0,1,1] neg_lo:[1,0,0] neg_hi:[1,0,0]
	v_pk_fma_f32 v[8:9], v[70:71], v[22:23], v[90:91] op_sel:[1,0,0] op_sel_hi:[1,1,1] neg_lo:[1,0,0] neg_hi:[1,0,0]
	s_waitcnt lgkmcnt(0)
	v_pk_mul_f32 v[22:23], v[2:3], v[36:37] op_sel:[0,0] op_sel_hi:[1,0]
	v_pk_mul_f32 v[58:59], v[2:3], v[76:77] op_sel:[0,0] op_sel_hi:[1,0]
	ds_read_b128 v[60:63], v20 offset:2304
	v_pk_fma_f32 v[22:23], v[4:5], v[36:37], v[22:23] op_sel:[0,1,0] op_sel_hi:[1,1,1]
	v_pk_mul_f32 v[84:85], v[4:5], v[76:77] op_sel:[0,1] op_sel_hi:[1,1]
	ds_read_b128 v[64:67], v20 offset:10496
	v_pk_fma_f32 v[22:23], v[6:7], v[38:39], v[22:23] op_sel:[0,0,0] op_sel_hi:[1,0,1]
	v_pk_fma_f32 v[58:59], v[6:7], v[78:79], v[58:59] op_sel:[0,0,0] op_sel_hi:[1,0,1]
	ds_read_b64 v[80:81], v21 offset:43264
	v_pk_fma_f32 v[22:23], v[8:9], v[38:39], v[22:23] op_sel:[0,1,0] op_sel_hi:[1,1,1]
	v_pk_fma_f32 v[84:85], v[8:9], v[78:79], v[84:85] op_sel:[0,1,0] op_sel_hi:[1,1,1]
	ds_read_b128 v[72:75], v20 offset:26880
	v_pk_add_f32 v[58:59], v[58:59], v[84:85]
	ds_read_b128 v[68:71], v20 offset:18688
	ds_read_b128 v[76:79], v20 offset:35072
	v_add_f32_dpp v24, v24, v24 row_ror:8 row_mask:0xf bank_mask:0x3
	v_add_f32_dpp v26, v26, v26 row_ror:8 row_mask:0xf bank_mask:0xc
	v_add_f32_dpp v22, v22, v22 quad_perm:[1,0,3,2] row_mask:0xf bank_mask:0xf
	v_add_f32_dpp v23, v23, v23 quad_perm:[1,0,3,2] row_mask:0xf bank_mask:0xf
	v_pk_mul_f32 v[84:85], v[2:3], v[40:41] op_sel:[0,0] op_sel_hi:[1,0]
	v_pk_mul_f32 v[86:87], v[4:5], v[40:41] op_sel:[0,1] op_sel_hi:[1,1]
	v_mov_b32_dpp v24, v26 quad_perm:[0,1,2,3] row_mask:0xf bank_mask:0xc
	v_add_f32_dpp v22, v22, v22 quad_perm:[2,3,0,1] row_mask:0xf bank_mask:0xf
	v_add_f32_dpp v23, v23, v23 quad_perm:[2,3,0,1] row_mask:0xf bank_mask:0xf
	v_pk_mul_f32 v[88:89], v[6:7], v[42:43] op_sel:[0,0] op_sel_hi:[1,0]
	v_pk_mul_f32 v[90:91], v[8:9], v[42:43] op_sel:[0,1] op_sel_hi:[1,1]
	v_add_f32_dpp v24, v24, v24 quad_perm:[1,0,3,2] row_mask:0xf bank_mask:0xf
	v_add_f32_dpp v22, v22, v22 row_half_mirror row_mask:0xf bank_mask:0xf
	v_add_f32_dpp v23, v23, v23 row_half_mirror row_mask:0xf bank_mask:0xf
	v_pk_fma_f32 v[84:85], v[48:49], v[56:57], v[84:85] op_sel:[0,0,0] op_sel_hi:[0,1,1]
	v_pk_fma_f32 v[86:87], v[48:49], v[56:57], v[86:87] op_sel:[1,0,0] op_sel_hi:[1,1,1]
	v_add_f32_dpp v24, v24, v24 quad_perm:[2,3,0,1] row_mask:0xf bank_mask:0xf
	v_add_f32_dpp v22, v22, v22 row_mirror row_mask:0xf bank_mask:0xf
	v_add_f32_dpp v23, v23, v23 row_mirror row_mask:0xf bank_mask:0xf
	v_pk_fma_f32 v[88:89], v[50:51], v[56:57], v[88:89] op_sel:[0,0,0] op_sel_hi:[0,1,1]
	v_pk_fma_f32 v[90:91], v[50:51], v[56:57], v[90:91] op_sel:[1,0,0] op_sel_hi:[1,1,1]
	v_cndmask_b32_e64 v30, v30, v24, s[8:9]
	v_pk_fma_f32 v[2:3], v[44:45], v[22:23], v[84:85] op_sel:[0,0,0] op_sel_hi:[0,1,1] neg_lo:[1,0,0] neg_hi:[1,0,0]
	v_pk_fma_f32 v[4:5], v[44:45], v[22:23], v[86:87] op_sel:[1,0,0] op_sel_hi:[1,1,1] neg_lo:[1,0,0] neg_hi:[1,0,0]
	v_pk_fma_f32 v[6:7], v[46:47], v[22:23], v[88:89] op_sel:[0,0,0] op_sel_hi:[0,1,1] neg_lo:[1,0,0] neg_hi:[1,0,0]
	v_pk_fma_f32 v[8:9], v[46:47], v[22:23], v[90:91] op_sel:[1,0,0] op_sel_hi:[1,1,1] neg_lo:[1,0,0] neg_hi:[1,0,0]
	s_waitcnt lgkmcnt(0)
	v_pk_mul_f32 v[22:23], v[2:3], v[60:61] op_sel:[0,0] op_sel_hi:[1,0]
	v_pk_mul_f32 v[24:25], v[2:3], v[52:53] op_sel:[0,0] op_sel_hi:[1,0]
	ds_read_b128 v[36:39], v20 offset:2560
	v_pk_fma_f32 v[22:23], v[4:5], v[60:61], v[22:23] op_sel:[0,1,0] op_sel_hi:[1,1,1]
	v_pk_mul_f32 v[84:85], v[4:5], v[52:53] op_sel:[0,1] op_sel_hi:[1,1]
	ds_read_b128 v[40:43], v20 offset:10752
	v_pk_fma_f32 v[22:23], v[6:7], v[62:63], v[22:23] op_sel:[0,0,0] op_sel_hi:[1,0,1]
	v_pk_fma_f32 v[24:25], v[6:7], v[54:55], v[24:25] op_sel:[0,0,0] op_sel_hi:[1,0,1]
	ds_read_b64 v[56:57], v21 offset:43520
	v_pk_fma_f32 v[22:23], v[8:9], v[62:63], v[22:23] op_sel:[0,1,0] op_sel_hi:[1,1,1]
	v_pk_fma_f32 v[84:85], v[8:9], v[54:55], v[84:85] op_sel:[0,1,0] op_sel_hi:[1,1,1]
	ds_read_b128 v[48:51], v20 offset:27136
	v_pk_add_f32 v[24:25], v[24:25], v[84:85]
	ds_read_b128 v[44:47], v20 offset:18944
	ds_read_b128 v[52:55], v20 offset:35328
	v_add_f32_dpp v28, v28, v28 row_ror:12 row_mask:0xf bank_mask:0x5
	v_add_f32_dpp v29, v29, v29 row_ror:4 row_mask:0xf bank_mask:0xa
	v_add_f32_dpp v22, v22, v22 quad_perm:[1,0,3,2] row_mask:0xf bank_mask:0xf
	v_add_f32_dpp v23, v23, v23 quad_perm:[1,0,3,2] row_mask:0xf bank_mask:0xf
	v_pk_mul_f32 v[84:85], v[2:3], v[64:65] op_sel:[0,0] op_sel_hi:[1,0]
	v_pk_mul_f32 v[86:87], v[4:5], v[64:65] op_sel:[0,1] op_sel_hi:[1,1]
	v_add_f32_dpp v58, v58, v58 row_ror:12 row_mask:0xf bank_mask:0x5
	v_add_f32_dpp v22, v22, v22 quad_perm:[2,3,0,1] row_mask:0xf bank_mask:0xf
	v_add_f32_dpp v23, v23, v23 quad_perm:[2,3,0,1] row_mask:0xf bank_mask:0xf
	v_pk_mul_f32 v[88:89], v[6:7], v[66:67] op_sel:[0,0] op_sel_hi:[1,0]
	v_pk_mul_f32 v[90:91], v[8:9], v[66:67] op_sel:[0,1] op_sel_hi:[1,1]
	v_add_f32_dpp v59, v59, v59 row_ror:4 row_mask:0xf bank_mask:0xa
	v_add_f32_dpp v22, v22, v22 row_half_mirror row_mask:0xf bank_mask:0xf
	v_add_f32_dpp v23, v23, v23 row_half_mirror row_mask:0xf bank_mask:0xf
	v_pk_fma_f32 v[84:85], v[72:73], v[80:81], v[84:85] op_sel:[0,0,0] op_sel_hi:[0,1,1]
	v_pk_fma_f32 v[86:87], v[72:73], v[80:81], v[86:87] op_sel:[1,0,0] op_sel_hi:[1,1,1]
	v_mov_b32_dpp v28, v29 quad_perm:[0,1,2,3] row_mask:0xf bank_mask:0xa
	v_add_f32_dpp v22, v22, v22 row_mirror row_mask:0xf bank_mask:0xf
	v_add_f32_dpp v23, v23, v23 row_mirror row_mask:0xf bank_mask:0xf
	v_pk_fma_f32 v[88:89], v[74:75], v[80:81], v[88:89] op_sel:[0,0,0] op_sel_hi:[0,1,1]
	v_pk_fma_f32 v[90:91], v[74:75], v[80:81], v[90:91] op_sel:[1,0,0] op_sel_hi:[1,1,1]
	v_mov_b32_dpp v58, v59 quad_perm:[0,1,2,3] row_mask:0xf bank_mask:0xa
	v_pk_fma_f32 v[2:3], v[68:69], v[22:23], v[84:85] op_sel:[0,0,0] op_sel_hi:[0,1,1] neg_lo:[1,0,0] neg_hi:[1,0,0]
	v_pk_fma_f32 v[4:5], v[68:69], v[22:23], v[86:87] op_sel:[1,0,0] op_sel_hi:[1,1,1] neg_lo:[1,0,0] neg_hi:[1,0,0]
	v_pk_fma_f32 v[6:7], v[70:71], v[22:23], v[88:89] op_sel:[0,0,0] op_sel_hi:[0,1,1] neg_lo:[1,0,0] neg_hi:[1,0,0]
	v_pk_fma_f32 v[8:9], v[70:71], v[22:23], v[90:91] op_sel:[1,0,0] op_sel_hi:[1,1,1] neg_lo:[1,0,0] neg_hi:[1,0,0]
	s_waitcnt lgkmcnt(0)
	v_pk_mul_f32 v[22:23], v[2:3], v[36:37] op_sel:[0,0] op_sel_hi:[1,0]
	v_pk_mul_f32 v[26:27], v[2:3], v[76:77] op_sel:[0,0] op_sel_hi:[1,0]
	ds_read_b128 v[60:63], v20 offset:2816
	v_pk_fma_f32 v[22:23], v[4:5], v[36:37], v[22:23] op_sel:[0,1,0] op_sel_hi:[1,1,1]
	v_pk_mul_f32 v[84:85], v[4:5], v[76:77] op_sel:[0,1] op_sel_hi:[1,1]
	ds_read_b128 v[64:67], v20 offset:11008
	v_pk_fma_f32 v[22:23], v[6:7], v[38:39], v[22:23] op_sel:[0,0,0] op_sel_hi:[1,0,1]
	v_pk_fma_f32 v[26:27], v[6:7], v[78:79], v[26:27] op_sel:[0,0,0] op_sel_hi:[1,0,1]
	ds_read_b64 v[80:81], v21 offset:43776
	v_pk_fma_f32 v[22:23], v[8:9], v[38:39], v[22:23] op_sel:[0,1,0] op_sel_hi:[1,1,1]
	v_pk_fma_f32 v[84:85], v[8:9], v[78:79], v[84:85] op_sel:[0,1,0] op_sel_hi:[1,1,1]
	ds_read_b128 v[72:75], v20 offset:27392
	v_pk_add_f32 v[26:27], v[26:27], v[84:85]
	ds_read_b128 v[68:71], v20 offset:19200
	ds_read_b128 v[76:79], v20 offset:35584
	v_add_f32_dpp v28, v28, v28 row_ror:8 row_mask:0xf bank_mask:0x3
	v_add_f32_dpp v58, v58, v58 row_ror:8 row_mask:0xf bank_mask:0xc
	v_add_f32_dpp v22, v22, v22 quad_perm:[1,0,3,2] row_mask:0xf bank_mask:0xf
	v_add_f32_dpp v23, v23, v23 quad_perm:[1,0,3,2] row_mask:0xf bank_mask:0xf
	v_pk_mul_f32 v[84:85], v[2:3], v[40:41] op_sel:[0,0] op_sel_hi:[1,0]
	v_pk_mul_f32 v[86:87], v[4:5], v[40:41] op_sel:[0,1] op_sel_hi:[1,1]
	v_mov_b32_dpp v28, v58 quad_perm:[0,1,2,3] row_mask:0xf bank_mask:0xc
	v_add_f32_dpp v22, v22, v22 quad_perm:[2,3,0,1] row_mask:0xf bank_mask:0xf
	v_add_f32_dpp v23, v23, v23 quad_perm:[2,3,0,1] row_mask:0xf bank_mask:0xf
	v_pk_mul_f32 v[88:89], v[6:7], v[42:43] op_sel:[0,0] op_sel_hi:[1,0]
	v_pk_mul_f32 v[90:91], v[8:9], v[42:43] op_sel:[0,1] op_sel_hi:[1,1]
	v_add_f32_dpp v28, v28, v28 quad_perm:[1,0,3,2] row_mask:0xf bank_mask:0xf
	v_add_f32_dpp v22, v22, v22 row_half_mirror row_mask:0xf bank_mask:0xf
	v_add_f32_dpp v23, v23, v23 row_half_mirror row_mask:0xf bank_mask:0xf
	v_pk_fma_f32 v[84:85], v[48:49], v[56:57], v[84:85] op_sel:[0,0,0] op_sel_hi:[0,1,1]
	v_pk_fma_f32 v[86:87], v[48:49], v[56:57], v[86:87] op_sel:[1,0,0] op_sel_hi:[1,1,1]
	v_add_f32_dpp v28, v28, v28 quad_perm:[2,3,0,1] row_mask:0xf bank_mask:0xf
	v_add_f32_dpp v22, v22, v22 row_mirror row_mask:0xf bank_mask:0xf
	v_add_f32_dpp v23, v23, v23 row_mirror row_mask:0xf bank_mask:0xf
	v_pk_fma_f32 v[88:89], v[50:51], v[56:57], v[88:89] op_sel:[0,0,0] op_sel_hi:[0,1,1]
	v_pk_fma_f32 v[90:91], v[50:51], v[56:57], v[90:91] op_sel:[1,0,0] op_sel_hi:[1,1,1]
	v_cndmask_b32_e64 v30, v30, v28, s[10:11]
	v_pk_fma_f32 v[2:3], v[44:45], v[22:23], v[84:85] op_sel:[0,0,0] op_sel_hi:[0,1,1] neg_lo:[1,0,0] neg_hi:[1,0,0]
	v_pk_fma_f32 v[4:5], v[44:45], v[22:23], v[86:87] op_sel:[1,0,0] op_sel_hi:[1,1,1] neg_lo:[1,0,0] neg_hi:[1,0,0]
	v_pk_fma_f32 v[6:7], v[46:47], v[22:23], v[88:89] op_sel:[0,0,0] op_sel_hi:[0,1,1] neg_lo:[1,0,0] neg_hi:[1,0,0]
	v_pk_fma_f32 v[8:9], v[46:47], v[22:23], v[90:91] op_sel:[1,0,0] op_sel_hi:[1,1,1] neg_lo:[1,0,0] neg_hi:[1,0,0]
	s_waitcnt lgkmcnt(0)
	v_pk_mul_f32 v[22:23], v[2:3], v[60:61] op_sel:[0,0] op_sel_hi:[1,0]
	v_pk_mul_f32 v[28:29], v[2:3], v[52:53] op_sel:[0,0] op_sel_hi:[1,0]
	ds_read_b128 v[36:39], v20 offset:3072
	v_pk_fma_f32 v[22:23], v[4:5], v[60:61], v[22:23] op_sel:[0,1,0] op_sel_hi:[1,1,1]
	v_pk_mul_f32 v[84:85], v[4:5], v[52:53] op_sel:[0,1] op_sel_hi:[1,1]
	ds_read_b128 v[40:43], v20 offset:11264
	v_pk_fma_f32 v[22:23], v[6:7], v[62:63], v[22:23] op_sel:[0,0,0] op_sel_hi:[1,0,1]
	v_pk_fma_f32 v[28:29], v[6:7], v[54:55], v[28:29] op_sel:[0,0,0] op_sel_hi:[1,0,1]
	ds_read_b64 v[56:57], v21 offset:44032
	v_pk_fma_f32 v[22:23], v[8:9], v[62:63], v[22:23] op_sel:[0,1,0] op_sel_hi:[1,1,1]
	v_pk_fma_f32 v[84:85], v[8:9], v[54:55], v[84:85] op_sel:[0,1,0] op_sel_hi:[1,1,1]
	ds_read_b128 v[48:51], v20 offset:27648
	v_pk_add_f32 v[28:29], v[28:29], v[84:85]
	ds_read_b128 v[44:47], v20 offset:19456
	ds_read_b128 v[52:55], v20 offset:35840
	v_add_f32_dpp v24, v24, v24 row_ror:12 row_mask:0xf bank_mask:0x5
	v_add_f32_dpp v25, v25, v25 row_ror:4 row_mask:0xf bank_mask:0xa
	v_add_f32_dpp v22, v22, v22 quad_perm:[1,0,3,2] row_mask:0xf bank_mask:0xf
	v_add_f32_dpp v23, v23, v23 quad_perm:[1,0,3,2] row_mask:0xf bank_mask:0xf
	v_pk_mul_f32 v[84:85], v[2:3], v[64:65] op_sel:[0,0] op_sel_hi:[1,0]
	v_pk_mul_f32 v[86:87], v[4:5], v[64:65] op_sel:[0,1] op_sel_hi:[1,1]
	v_add_f32_dpp v26, v26, v26 row_ror:12 row_mask:0xf bank_mask:0x5
	v_add_f32_dpp v22, v22, v22 quad_perm:[2,3,0,1] row_mask:0xf bank_mask:0xf
	v_add_f32_dpp v23, v23, v23 quad_perm:[2,3,0,1] row_mask:0xf bank_mask:0xf
	v_pk_mul_f32 v[88:89], v[6:7], v[66:67] op_sel:[0,0] op_sel_hi:[1,0]
	v_pk_mul_f32 v[90:91], v[8:9], v[66:67] op_sel:[0,1] op_sel_hi:[1,1]
	v_add_f32_dpp v27, v27, v27 row_ror:4 row_mask:0xf bank_mask:0xa
	v_add_f32_dpp v22, v22, v22 row_half_mirror row_mask:0xf bank_mask:0xf
	v_add_f32_dpp v23, v23, v23 row_half_mirror row_mask:0xf bank_mask:0xf
	v_pk_fma_f32 v[84:85], v[72:73], v[80:81], v[84:85] op_sel:[0,0,0] op_sel_hi:[0,1,1]
	v_pk_fma_f32 v[86:87], v[72:73], v[80:81], v[86:87] op_sel:[1,0,0] op_sel_hi:[1,1,1]
	v_mov_b32_dpp v24, v25 quad_perm:[0,1,2,3] row_mask:0xf bank_mask:0xa
	v_add_f32_dpp v22, v22, v22 row_mirror row_mask:0xf bank_mask:0xf
	v_add_f32_dpp v23, v23, v23 row_mirror row_mask:0xf bank_mask:0xf
	v_pk_fma_f32 v[88:89], v[74:75], v[80:81], v[88:89] op_sel:[0,0,0] op_sel_hi:[0,1,1]
	v_pk_fma_f32 v[90:91], v[74:75], v[80:81], v[90:91] op_sel:[1,0,0] op_sel_hi:[1,1,1]
	v_mov_b32_dpp v26, v27 quad_perm:[0,1,2,3] row_mask:0xf bank_mask:0xa
	v_pk_fma_f32 v[2:3], v[68:69], v[22:23], v[84:85] op_sel:[0,0,0] op_sel_hi:[0,1,1] neg_lo:[1,0,0] neg_hi:[1,0,0]
	v_pk_fma_f32 v[4:5], v[68:69], v[22:23], v[86:87] op_sel:[1,0,0] op_sel_hi:[1,1,1] neg_lo:[1,0,0] neg_hi:[1,0,0]
	v_pk_fma_f32 v[6:7], v[70:71], v[22:23], v[88:89] op_sel:[0,0,0] op_sel_hi:[0,1,1] neg_lo:[1,0,0] neg_hi:[1,0,0]
	v_pk_fma_f32 v[8:9], v[70:71], v[22:23], v[90:91] op_sel:[1,0,0] op_sel_hi:[1,1,1] neg_lo:[1,0,0] neg_hi:[1,0,0]
	s_waitcnt lgkmcnt(0)
	v_pk_mul_f32 v[22:23], v[2:3], v[36:37] op_sel:[0,0] op_sel_hi:[1,0]
	v_pk_mul_f32 v[58:59], v[2:3], v[76:77] op_sel:[0,0] op_sel_hi:[1,0]
	ds_read_b128 v[60:63], v20 offset:3328
	v_pk_fma_f32 v[22:23], v[4:5], v[36:37], v[22:23] op_sel:[0,1,0] op_sel_hi:[1,1,1]
	v_pk_mul_f32 v[84:85], v[4:5], v[76:77] op_sel:[0,1] op_sel_hi:[1,1]
	ds_read_b128 v[64:67], v20 offset:11520
	v_pk_fma_f32 v[22:23], v[6:7], v[38:39], v[22:23] op_sel:[0,0,0] op_sel_hi:[1,0,1]
	v_pk_fma_f32 v[58:59], v[6:7], v[78:79], v[58:59] op_sel:[0,0,0] op_sel_hi:[1,0,1]
	ds_read_b64 v[80:81], v21 offset:44288
	v_pk_fma_f32 v[22:23], v[8:9], v[38:39], v[22:23] op_sel:[0,1,0] op_sel_hi:[1,1,1]
	v_pk_fma_f32 v[84:85], v[8:9], v[78:79], v[84:85] op_sel:[0,1,0] op_sel_hi:[1,1,1]
	ds_read_b128 v[72:75], v20 offset:27904
	v_pk_add_f32 v[58:59], v[58:59], v[84:85]
	ds_read_b128 v[68:71], v20 offset:19712
	ds_read_b128 v[76:79], v20 offset:36096
	v_add_f32_dpp v24, v24, v24 row_ror:8 row_mask:0xf bank_mask:0x3
	v_add_f32_dpp v26, v26, v26 row_ror:8 row_mask:0xf bank_mask:0xc
	v_add_f32_dpp v22, v22, v22 quad_perm:[1,0,3,2] row_mask:0xf bank_mask:0xf
	v_add_f32_dpp v23, v23, v23 quad_perm:[1,0,3,2] row_mask:0xf bank_mask:0xf
	v_pk_mul_f32 v[84:85], v[2:3], v[40:41] op_sel:[0,0] op_sel_hi:[1,0]
	v_pk_mul_f32 v[86:87], v[4:5], v[40:41] op_sel:[0,1] op_sel_hi:[1,1]
	v_mov_b32_dpp v24, v26 quad_perm:[0,1,2,3] row_mask:0xf bank_mask:0xc
	v_add_f32_dpp v22, v22, v22 quad_perm:[2,3,0,1] row_mask:0xf bank_mask:0xf
	v_add_f32_dpp v23, v23, v23 quad_perm:[2,3,0,1] row_mask:0xf bank_mask:0xf
	v_pk_mul_f32 v[88:89], v[6:7], v[42:43] op_sel:[0,0] op_sel_hi:[1,0]
	v_pk_mul_f32 v[90:91], v[8:9], v[42:43] op_sel:[0,1] op_sel_hi:[1,1]
	v_add_f32_dpp v24, v24, v24 quad_perm:[1,0,3,2] row_mask:0xf bank_mask:0xf
	v_add_f32_dpp v22, v22, v22 row_half_mirror row_mask:0xf bank_mask:0xf
	v_add_f32_dpp v23, v23, v23 row_half_mirror row_mask:0xf bank_mask:0xf
	v_pk_fma_f32 v[84:85], v[48:49], v[56:57], v[84:85] op_sel:[0,0,0] op_sel_hi:[0,1,1]
	v_pk_fma_f32 v[86:87], v[48:49], v[56:57], v[86:87] op_sel:[1,0,0] op_sel_hi:[1,1,1]
	v_add_f32_dpp v24, v24, v24 quad_perm:[2,3,0,1] row_mask:0xf bank_mask:0xf
	v_add_f32_dpp v22, v22, v22 row_mirror row_mask:0xf bank_mask:0xf
	v_add_f32_dpp v23, v23, v23 row_mirror row_mask:0xf bank_mask:0xf
	v_pk_fma_f32 v[88:89], v[50:51], v[56:57], v[88:89] op_sel:[0,0,0] op_sel_hi:[0,1,1]
	v_pk_fma_f32 v[90:91], v[50:51], v[56:57], v[90:91] op_sel:[1,0,0] op_sel_hi:[1,1,1]
	v_cndmask_b32_e64 v31, 0, v24, s[0:1]
	v_pk_fma_f32 v[2:3], v[44:45], v[22:23], v[84:85] op_sel:[0,0,0] op_sel_hi:[0,1,1] neg_lo:[1,0,0] neg_hi:[1,0,0]
	v_pk_fma_f32 v[4:5], v[44:45], v[22:23], v[86:87] op_sel:[1,0,0] op_sel_hi:[1,1,1] neg_lo:[1,0,0] neg_hi:[1,0,0]
	v_pk_fma_f32 v[6:7], v[46:47], v[22:23], v[88:89] op_sel:[0,0,0] op_sel_hi:[0,1,1] neg_lo:[1,0,0] neg_hi:[1,0,0]
	v_pk_fma_f32 v[8:9], v[46:47], v[22:23], v[90:91] op_sel:[1,0,0] op_sel_hi:[1,1,1] neg_lo:[1,0,0] neg_hi:[1,0,0]
	s_waitcnt lgkmcnt(0)
	v_pk_mul_f32 v[22:23], v[2:3], v[60:61] op_sel:[0,0] op_sel_hi:[1,0]
	v_pk_mul_f32 v[24:25], v[2:3], v[52:53] op_sel:[0,0] op_sel_hi:[1,0]
	ds_read_b128 v[36:39], v20 offset:3584
	v_pk_fma_f32 v[22:23], v[4:5], v[60:61], v[22:23] op_sel:[0,1,0] op_sel_hi:[1,1,1]
	v_pk_mul_f32 v[84:85], v[4:5], v[52:53] op_sel:[0,1] op_sel_hi:[1,1]
	ds_read_b128 v[40:43], v20 offset:11776
	v_pk_fma_f32 v[22:23], v[6:7], v[62:63], v[22:23] op_sel:[0,0,0] op_sel_hi:[1,0,1]
	v_pk_fma_f32 v[24:25], v[6:7], v[54:55], v[24:25] op_sel:[0,0,0] op_sel_hi:[1,0,1]
	ds_read_b64 v[56:57], v21 offset:44544
	v_pk_fma_f32 v[22:23], v[8:9], v[62:63], v[22:23] op_sel:[0,1,0] op_sel_hi:[1,1,1]
	v_pk_fma_f32 v[84:85], v[8:9], v[54:55], v[84:85] op_sel:[0,1,0] op_sel_hi:[1,1,1]
	ds_read_b128 v[48:51], v20 offset:28160
	v_pk_add_f32 v[24:25], v[24:25], v[84:85]
	ds_read_b128 v[44:47], v20 offset:19968
	ds_read_b128 v[52:55], v20 offset:36352
	v_add_f32_dpp v28, v28, v28 row_ror:12 row_mask:0xf bank_mask:0x5
	v_add_f32_dpp v29, v29, v29 row_ror:4 row_mask:0xf bank_mask:0xa
	v_add_f32_dpp v22, v22, v22 quad_perm:[1,0,3,2] row_mask:0xf bank_mask:0xf
	v_add_f32_dpp v23, v23, v23 quad_perm:[1,0,3,2] row_mask:0xf bank_mask:0xf
	v_pk_mul_f32 v[84:85], v[2:3], v[64:65] op_sel:[0,0] op_sel_hi:[1,0]
	v_pk_mul_f32 v[86:87], v[4:5], v[64:65] op_sel:[0,1] op_sel_hi:[1,1]
	v_add_f32_dpp v58, v58, v58 row_ror:12 row_mask:0xf bank_mask:0x5
	v_add_f32_dpp v22, v22, v22 quad_perm:[2,3,0,1] row_mask:0xf bank_mask:0xf
	v_add_f32_dpp v23, v23, v23 quad_perm:[2,3,0,1] row_mask:0xf bank_mask:0xf
	v_pk_mul_f32 v[88:89], v[6:7], v[66:67] op_sel:[0,0] op_sel_hi:[1,0]
	v_pk_mul_f32 v[90:91], v[8:9], v[66:67] op_sel:[0,1] op_sel_hi:[1,1]
	v_add_f32_dpp v59, v59, v59 row_ror:4 row_mask:0xf bank_mask:0xa
	v_add_f32_dpp v22, v22, v22 row_half_mirror row_mask:0xf bank_mask:0xf
	v_add_f32_dpp v23, v23, v23 row_half_mirror row_mask:0xf bank_mask:0xf
	v_pk_fma_f32 v[84:85], v[72:73], v[80:81], v[84:85] op_sel:[0,0,0] op_sel_hi:[0,1,1]
	v_pk_fma_f32 v[86:87], v[72:73], v[80:81], v[86:87] op_sel:[1,0,0] op_sel_hi:[1,1,1]
	v_mov_b32_dpp v28, v29 quad_perm:[0,1,2,3] row_mask:0xf bank_mask:0xa
	v_add_f32_dpp v22, v22, v22 row_mirror row_mask:0xf bank_mask:0xf
	v_add_f32_dpp v23, v23, v23 row_mirror row_mask:0xf bank_mask:0xf
	v_pk_fma_f32 v[88:89], v[74:75], v[80:81], v[88:89] op_sel:[0,0,0] op_sel_hi:[0,1,1]
	v_pk_fma_f32 v[90:91], v[74:75], v[80:81], v[90:91] op_sel:[1,0,0] op_sel_hi:[1,1,1]
	v_mov_b32_dpp v58, v59 quad_perm:[0,1,2,3] row_mask:0xf bank_mask:0xa
	v_pk_fma_f32 v[2:3], v[68:69], v[22:23], v[84:85] op_sel:[0,0,0] op_sel_hi:[0,1,1] neg_lo:[1,0,0] neg_hi:[1,0,0]
	v_pk_fma_f32 v[4:5], v[68:69], v[22:23], v[86:87] op_sel:[1,0,0] op_sel_hi:[1,1,1] neg_lo:[1,0,0] neg_hi:[1,0,0]
	v_pk_fma_f32 v[6:7], v[70:71], v[22:23], v[88:89] op_sel:[0,0,0] op_sel_hi:[0,1,1] neg_lo:[1,0,0] neg_hi:[1,0,0]
	v_pk_fma_f32 v[8:9], v[70:71], v[22:23], v[90:91] op_sel:[1,0,0] op_sel_hi:[1,1,1] neg_lo:[1,0,0] neg_hi:[1,0,0]
	s_waitcnt lgkmcnt(0)
	v_pk_mul_f32 v[22:23], v[2:3], v[36:37] op_sel:[0,0] op_sel_hi:[1,0]
	v_pk_mul_f32 v[26:27], v[2:3], v[76:77] op_sel:[0,0] op_sel_hi:[1,0]
	ds_read_b128 v[60:63], v20 offset:3840
	v_pk_fma_f32 v[22:23], v[4:5], v[36:37], v[22:23] op_sel:[0,1,0] op_sel_hi:[1,1,1]
	v_pk_mul_f32 v[84:85], v[4:5], v[76:77] op_sel:[0,1] op_sel_hi:[1,1]
	ds_read_b128 v[64:67], v20 offset:12032
	v_pk_fma_f32 v[22:23], v[6:7], v[38:39], v[22:23] op_sel:[0,0,0] op_sel_hi:[1,0,1]
	v_pk_fma_f32 v[26:27], v[6:7], v[78:79], v[26:27] op_sel:[0,0,0] op_sel_hi:[1,0,1]
	ds_read_b64 v[80:81], v21 offset:44800
	v_pk_fma_f32 v[22:23], v[8:9], v[38:39], v[22:23] op_sel:[0,1,0] op_sel_hi:[1,1,1]
	v_pk_fma_f32 v[84:85], v[8:9], v[78:79], v[84:85] op_sel:[0,1,0] op_sel_hi:[1,1,1]
	ds_read_b128 v[72:75], v20 offset:28416
	v_pk_add_f32 v[26:27], v[26:27], v[84:85]
	ds_read_b128 v[68:71], v20 offset:20224
	ds_read_b128 v[76:79], v20 offset:36608
	v_add_f32_dpp v28, v28, v28 row_ror:8 row_mask:0xf bank_mask:0x3
	v_add_f32_dpp v58, v58, v58 row_ror:8 row_mask:0xf bank_mask:0xc
	v_add_f32_dpp v22, v22, v22 quad_perm:[1,0,3,2] row_mask:0xf bank_mask:0xf
	v_add_f32_dpp v23, v23, v23 quad_perm:[1,0,3,2] row_mask:0xf bank_mask:0xf
	v_pk_mul_f32 v[84:85], v[2:3], v[40:41] op_sel:[0,0] op_sel_hi:[1,0]
	v_pk_mul_f32 v[86:87], v[4:5], v[40:41] op_sel:[0,1] op_sel_hi:[1,1]
	v_mov_b32_dpp v28, v58 quad_perm:[0,1,2,3] row_mask:0xf bank_mask:0xc
	v_add_f32_dpp v22, v22, v22 quad_perm:[2,3,0,1] row_mask:0xf bank_mask:0xf
	v_add_f32_dpp v23, v23, v23 quad_perm:[2,3,0,1] row_mask:0xf bank_mask:0xf
	v_pk_mul_f32 v[88:89], v[6:7], v[42:43] op_sel:[0,0] op_sel_hi:[1,0]
	v_pk_mul_f32 v[90:91], v[8:9], v[42:43] op_sel:[0,1] op_sel_hi:[1,1]
	v_add_f32_dpp v28, v28, v28 quad_perm:[1,0,3,2] row_mask:0xf bank_mask:0xf
	v_add_f32_dpp v22, v22, v22 row_half_mirror row_mask:0xf bank_mask:0xf
	v_add_f32_dpp v23, v23, v23 row_half_mirror row_mask:0xf bank_mask:0xf
	v_pk_fma_f32 v[84:85], v[48:49], v[56:57], v[84:85] op_sel:[0,0,0] op_sel_hi:[0,1,1]
	v_pk_fma_f32 v[86:87], v[48:49], v[56:57], v[86:87] op_sel:[1,0,0] op_sel_hi:[1,1,1]
	v_add_f32_dpp v28, v28, v28 quad_perm:[2,3,0,1] row_mask:0xf bank_mask:0xf
	v_add_f32_dpp v22, v22, v22 row_mirror row_mask:0xf bank_mask:0xf
	v_add_f32_dpp v23, v23, v23 row_mirror row_mask:0xf bank_mask:0xf
	v_pk_fma_f32 v[88:89], v[50:51], v[56:57], v[88:89] op_sel:[0,0,0] op_sel_hi:[0,1,1]
	v_pk_fma_f32 v[90:91], v[50:51], v[56:57], v[90:91] op_sel:[1,0,0] op_sel_hi:[1,1,1]
	v_cndmask_b32_e64 v31, v31, v28, s[6:7]
	v_pk_fma_f32 v[2:3], v[44:45], v[22:23], v[84:85] op_sel:[0,0,0] op_sel_hi:[0,1,1] neg_lo:[1,0,0] neg_hi:[1,0,0]
	v_pk_fma_f32 v[4:5], v[44:45], v[22:23], v[86:87] op_sel:[1,0,0] op_sel_hi:[1,1,1] neg_lo:[1,0,0] neg_hi:[1,0,0]
	v_pk_fma_f32 v[6:7], v[46:47], v[22:23], v[88:89] op_sel:[0,0,0] op_sel_hi:[0,1,1] neg_lo:[1,0,0] neg_hi:[1,0,0]
	v_pk_fma_f32 v[8:9], v[46:47], v[22:23], v[90:91] op_sel:[1,0,0] op_sel_hi:[1,1,1] neg_lo:[1,0,0] neg_hi:[1,0,0]
	s_waitcnt lgkmcnt(0)
	v_pk_mul_f32 v[22:23], v[2:3], v[60:61] op_sel:[0,0] op_sel_hi:[1,0]
	v_pk_mul_f32 v[28:29], v[2:3], v[52:53] op_sel:[0,0] op_sel_hi:[1,0]
	ds_read_b128 v[36:39], v20 offset:4096
	v_pk_fma_f32 v[22:23], v[4:5], v[60:61], v[22:23] op_sel:[0,1,0] op_sel_hi:[1,1,1]
	v_pk_mul_f32 v[84:85], v[4:5], v[52:53] op_sel:[0,1] op_sel_hi:[1,1]
	ds_read_b128 v[40:43], v20 offset:12288
	v_pk_fma_f32 v[22:23], v[6:7], v[62:63], v[22:23] op_sel:[0,0,0] op_sel_hi:[1,0,1]
	v_pk_fma_f32 v[28:29], v[6:7], v[54:55], v[28:29] op_sel:[0,0,0] op_sel_hi:[1,0,1]
	ds_read_b64 v[56:57], v21 offset:45056
	v_pk_fma_f32 v[22:23], v[8:9], v[62:63], v[22:23] op_sel:[0,1,0] op_sel_hi:[1,1,1]
	v_pk_fma_f32 v[84:85], v[8:9], v[54:55], v[84:85] op_sel:[0,1,0] op_sel_hi:[1,1,1]
	ds_read_b128 v[48:51], v20 offset:28672
	v_pk_add_f32 v[28:29], v[28:29], v[84:85]
	ds_read_b128 v[44:47], v20 offset:20480
	ds_read_b128 v[52:55], v20 offset:36864
	v_add_f32_dpp v24, v24, v24 row_ror:12 row_mask:0xf bank_mask:0x5
	v_add_f32_dpp v25, v25, v25 row_ror:4 row_mask:0xf bank_mask:0xa
	v_add_f32_dpp v22, v22, v22 quad_perm:[1,0,3,2] row_mask:0xf bank_mask:0xf
	v_add_f32_dpp v23, v23, v23 quad_perm:[1,0,3,2] row_mask:0xf bank_mask:0xf
	v_pk_mul_f32 v[84:85], v[2:3], v[64:65] op_sel:[0,0] op_sel_hi:[1,0]
	v_pk_mul_f32 v[86:87], v[4:5], v[64:65] op_sel:[0,1] op_sel_hi:[1,1]
	v_add_f32_dpp v26, v26, v26 row_ror:12 row_mask:0xf bank_mask:0x5
	v_add_f32_dpp v22, v22, v22 quad_perm:[2,3,0,1] row_mask:0xf bank_mask:0xf
	v_add_f32_dpp v23, v23, v23 quad_perm:[2,3,0,1] row_mask:0xf bank_mask:0xf
	v_pk_mul_f32 v[88:89], v[6:7], v[66:67] op_sel:[0,0] op_sel_hi:[1,0]
	v_pk_mul_f32 v[90:91], v[8:9], v[66:67] op_sel:[0,1] op_sel_hi:[1,1]
	v_add_f32_dpp v27, v27, v27 row_ror:4 row_mask:0xf bank_mask:0xa
	v_add_f32_dpp v22, v22, v22 row_half_mirror row_mask:0xf bank_mask:0xf
	v_add_f32_dpp v23, v23, v23 row_half_mirror row_mask:0xf bank_mask:0xf
	v_pk_fma_f32 v[84:85], v[72:73], v[80:81], v[84:85] op_sel:[0,0,0] op_sel_hi:[0,1,1]
	v_pk_fma_f32 v[86:87], v[72:73], v[80:81], v[86:87] op_sel:[1,0,0] op_sel_hi:[1,1,1]
	v_mov_b32_dpp v24, v25 quad_perm:[0,1,2,3] row_mask:0xf bank_mask:0xa
	v_add_f32_dpp v22, v22, v22 row_mirror row_mask:0xf bank_mask:0xf
	v_add_f32_dpp v23, v23, v23 row_mirror row_mask:0xf bank_mask:0xf
	v_pk_fma_f32 v[88:89], v[74:75], v[80:81], v[88:89] op_sel:[0,0,0] op_sel_hi:[0,1,1]
	v_pk_fma_f32 v[90:91], v[74:75], v[80:81], v[90:91] op_sel:[1,0,0] op_sel_hi:[1,1,1]
	v_mov_b32_dpp v26, v27 quad_perm:[0,1,2,3] row_mask:0xf bank_mask:0xa
	v_pk_fma_f32 v[2:3], v[68:69], v[22:23], v[84:85] op_sel:[0,0,0] op_sel_hi:[0,1,1] neg_lo:[1,0,0] neg_hi:[1,0,0]
	v_pk_fma_f32 v[4:5], v[68:69], v[22:23], v[86:87] op_sel:[1,0,0] op_sel_hi:[1,1,1] neg_lo:[1,0,0] neg_hi:[1,0,0]
	v_pk_fma_f32 v[6:7], v[70:71], v[22:23], v[88:89] op_sel:[0,0,0] op_sel_hi:[0,1,1] neg_lo:[1,0,0] neg_hi:[1,0,0]
	v_pk_fma_f32 v[8:9], v[70:71], v[22:23], v[90:91] op_sel:[1,0,0] op_sel_hi:[1,1,1] neg_lo:[1,0,0] neg_hi:[1,0,0]
	s_waitcnt lgkmcnt(0)
	v_pk_mul_f32 v[22:23], v[2:3], v[36:37] op_sel:[0,0] op_sel_hi:[1,0]
	v_pk_mul_f32 v[58:59], v[2:3], v[76:77] op_sel:[0,0] op_sel_hi:[1,0]
	ds_read_b128 v[60:63], v20 offset:4352
	v_pk_fma_f32 v[22:23], v[4:5], v[36:37], v[22:23] op_sel:[0,1,0] op_sel_hi:[1,1,1]
	v_pk_mul_f32 v[84:85], v[4:5], v[76:77] op_sel:[0,1] op_sel_hi:[1,1]
	ds_read_b128 v[64:67], v20 offset:12544
	v_pk_fma_f32 v[22:23], v[6:7], v[38:39], v[22:23] op_sel:[0,0,0] op_sel_hi:[1,0,1]
	v_pk_fma_f32 v[58:59], v[6:7], v[78:79], v[58:59] op_sel:[0,0,0] op_sel_hi:[1,0,1]
	ds_read_b64 v[80:81], v21 offset:45312
	v_pk_fma_f32 v[22:23], v[8:9], v[38:39], v[22:23] op_sel:[0,1,0] op_sel_hi:[1,1,1]
	v_pk_fma_f32 v[84:85], v[8:9], v[78:79], v[84:85] op_sel:[0,1,0] op_sel_hi:[1,1,1]
	ds_read_b128 v[72:75], v20 offset:28928
	v_pk_add_f32 v[58:59], v[58:59], v[84:85]
	ds_read_b128 v[68:71], v20 offset:20736
	ds_read_b128 v[76:79], v20 offset:37120
	v_add_f32_dpp v24, v24, v24 row_ror:8 row_mask:0xf bank_mask:0x3
	v_add_f32_dpp v26, v26, v26 row_ror:8 row_mask:0xf bank_mask:0xc
	v_add_f32_dpp v22, v22, v22 quad_perm:[1,0,3,2] row_mask:0xf bank_mask:0xf
	v_add_f32_dpp v23, v23, v23 quad_perm:[1,0,3,2] row_mask:0xf bank_mask:0xf
	v_pk_mul_f32 v[84:85], v[2:3], v[40:41] op_sel:[0,0] op_sel_hi:[1,0]
	v_pk_mul_f32 v[86:87], v[4:5], v[40:41] op_sel:[0,1] op_sel_hi:[1,1]
	v_mov_b32_dpp v24, v26 quad_perm:[0,1,2,3] row_mask:0xf bank_mask:0xc
	v_add_f32_dpp v22, v22, v22 quad_perm:[2,3,0,1] row_mask:0xf bank_mask:0xf
	v_add_f32_dpp v23, v23, v23 quad_perm:[2,3,0,1] row_mask:0xf bank_mask:0xf
	v_pk_mul_f32 v[88:89], v[6:7], v[42:43] op_sel:[0,0] op_sel_hi:[1,0]
	v_pk_mul_f32 v[90:91], v[8:9], v[42:43] op_sel:[0,1] op_sel_hi:[1,1]
	v_add_f32_dpp v24, v24, v24 quad_perm:[1,0,3,2] row_mask:0xf bank_mask:0xf
	v_add_f32_dpp v22, v22, v22 row_half_mirror row_mask:0xf bank_mask:0xf
	v_add_f32_dpp v23, v23, v23 row_half_mirror row_mask:0xf bank_mask:0xf
	v_pk_fma_f32 v[84:85], v[48:49], v[56:57], v[84:85] op_sel:[0,0,0] op_sel_hi:[0,1,1]
	v_pk_fma_f32 v[86:87], v[48:49], v[56:57], v[86:87] op_sel:[1,0,0] op_sel_hi:[1,1,1]
	v_add_f32_dpp v24, v24, v24 quad_perm:[2,3,0,1] row_mask:0xf bank_mask:0xf
	v_add_f32_dpp v22, v22, v22 row_mirror row_mask:0xf bank_mask:0xf
	v_add_f32_dpp v23, v23, v23 row_mirror row_mask:0xf bank_mask:0xf
	v_pk_fma_f32 v[88:89], v[50:51], v[56:57], v[88:89] op_sel:[0,0,0] op_sel_hi:[0,1,1]
	v_pk_fma_f32 v[90:91], v[50:51], v[56:57], v[90:91] op_sel:[1,0,0] op_sel_hi:[1,1,1]
	v_cndmask_b32_e64 v31, v31, v24, s[8:9]
	v_pk_fma_f32 v[2:3], v[44:45], v[22:23], v[84:85] op_sel:[0,0,0] op_sel_hi:[0,1,1] neg_lo:[1,0,0] neg_hi:[1,0,0]
	v_pk_fma_f32 v[4:5], v[44:45], v[22:23], v[86:87] op_sel:[1,0,0] op_sel_hi:[1,1,1] neg_lo:[1,0,0] neg_hi:[1,0,0]
	v_pk_fma_f32 v[6:7], v[46:47], v[22:23], v[88:89] op_sel:[0,0,0] op_sel_hi:[0,1,1] neg_lo:[1,0,0] neg_hi:[1,0,0]
	v_pk_fma_f32 v[8:9], v[46:47], v[22:23], v[90:91] op_sel:[1,0,0] op_sel_hi:[1,1,1] neg_lo:[1,0,0] neg_hi:[1,0,0]
	s_waitcnt lgkmcnt(0)
	v_pk_mul_f32 v[22:23], v[2:3], v[60:61] op_sel:[0,0] op_sel_hi:[1,0]
	v_pk_mul_f32 v[24:25], v[2:3], v[52:53] op_sel:[0,0] op_sel_hi:[1,0]
	ds_read_b128 v[36:39], v20 offset:4608
	v_pk_fma_f32 v[22:23], v[4:5], v[60:61], v[22:23] op_sel:[0,1,0] op_sel_hi:[1,1,1]
	v_pk_mul_f32 v[84:85], v[4:5], v[52:53] op_sel:[0,1] op_sel_hi:[1,1]
	ds_read_b128 v[40:43], v20 offset:12800
	v_pk_fma_f32 v[22:23], v[6:7], v[62:63], v[22:23] op_sel:[0,0,0] op_sel_hi:[1,0,1]
	v_pk_fma_f32 v[24:25], v[6:7], v[54:55], v[24:25] op_sel:[0,0,0] op_sel_hi:[1,0,1]
	ds_read_b64 v[56:57], v21 offset:45568
	v_pk_fma_f32 v[22:23], v[8:9], v[62:63], v[22:23] op_sel:[0,1,0] op_sel_hi:[1,1,1]
	v_pk_fma_f32 v[84:85], v[8:9], v[54:55], v[84:85] op_sel:[0,1,0] op_sel_hi:[1,1,1]
	ds_read_b128 v[48:51], v20 offset:29184
	v_pk_add_f32 v[24:25], v[24:25], v[84:85]
	ds_read_b128 v[44:47], v20 offset:20992
	ds_read_b128 v[52:55], v20 offset:37376
	v_add_f32_dpp v28, v28, v28 row_ror:12 row_mask:0xf bank_mask:0x5
	v_add_f32_dpp v29, v29, v29 row_ror:4 row_mask:0xf bank_mask:0xa
	v_add_f32_dpp v22, v22, v22 quad_perm:[1,0,3,2] row_mask:0xf bank_mask:0xf
	v_add_f32_dpp v23, v23, v23 quad_perm:[1,0,3,2] row_mask:0xf bank_mask:0xf
	v_pk_mul_f32 v[84:85], v[2:3], v[64:65] op_sel:[0,0] op_sel_hi:[1,0]
	v_pk_mul_f32 v[86:87], v[4:5], v[64:65] op_sel:[0,1] op_sel_hi:[1,1]
	v_add_f32_dpp v58, v58, v58 row_ror:12 row_mask:0xf bank_mask:0x5
	v_add_f32_dpp v22, v22, v22 quad_perm:[2,3,0,1] row_mask:0xf bank_mask:0xf
	v_add_f32_dpp v23, v23, v23 quad_perm:[2,3,0,1] row_mask:0xf bank_mask:0xf
	v_pk_mul_f32 v[88:89], v[6:7], v[66:67] op_sel:[0,0] op_sel_hi:[1,0]
	v_pk_mul_f32 v[90:91], v[8:9], v[66:67] op_sel:[0,1] op_sel_hi:[1,1]
	v_add_f32_dpp v59, v59, v59 row_ror:4 row_mask:0xf bank_mask:0xa
	v_add_f32_dpp v22, v22, v22 row_half_mirror row_mask:0xf bank_mask:0xf
	v_add_f32_dpp v23, v23, v23 row_half_mirror row_mask:0xf bank_mask:0xf
	v_pk_fma_f32 v[84:85], v[72:73], v[80:81], v[84:85] op_sel:[0,0,0] op_sel_hi:[0,1,1]
	v_pk_fma_f32 v[86:87], v[72:73], v[80:81], v[86:87] op_sel:[1,0,0] op_sel_hi:[1,1,1]
	v_mov_b32_dpp v28, v29 quad_perm:[0,1,2,3] row_mask:0xf bank_mask:0xa
	v_add_f32_dpp v22, v22, v22 row_mirror row_mask:0xf bank_mask:0xf
	v_add_f32_dpp v23, v23, v23 row_mirror row_mask:0xf bank_mask:0xf
	v_pk_fma_f32 v[88:89], v[74:75], v[80:81], v[88:89] op_sel:[0,0,0] op_sel_hi:[0,1,1]
	v_pk_fma_f32 v[90:91], v[74:75], v[80:81], v[90:91] op_sel:[1,0,0] op_sel_hi:[1,1,1]
	v_mov_b32_dpp v58, v59 quad_perm:[0,1,2,3] row_mask:0xf bank_mask:0xa
	v_pk_fma_f32 v[2:3], v[68:69], v[22:23], v[84:85] op_sel:[0,0,0] op_sel_hi:[0,1,1] neg_lo:[1,0,0] neg_hi:[1,0,0]
	v_pk_fma_f32 v[4:5], v[68:69], v[22:23], v[86:87] op_sel:[1,0,0] op_sel_hi:[1,1,1] neg_lo:[1,0,0] neg_hi:[1,0,0]
	v_pk_fma_f32 v[6:7], v[70:71], v[22:23], v[88:89] op_sel:[0,0,0] op_sel_hi:[0,1,1] neg_lo:[1,0,0] neg_hi:[1,0,0]
	v_pk_fma_f32 v[8:9], v[70:71], v[22:23], v[90:91] op_sel:[1,0,0] op_sel_hi:[1,1,1] neg_lo:[1,0,0] neg_hi:[1,0,0]
	s_waitcnt lgkmcnt(0)
	v_pk_mul_f32 v[22:23], v[2:3], v[36:37] op_sel:[0,0] op_sel_hi:[1,0]
	v_pk_mul_f32 v[26:27], v[2:3], v[76:77] op_sel:[0,0] op_sel_hi:[1,0]
	ds_read_b128 v[60:63], v20 offset:4864
	v_pk_fma_f32 v[22:23], v[4:5], v[36:37], v[22:23] op_sel:[0,1,0] op_sel_hi:[1,1,1]
	v_pk_mul_f32 v[84:85], v[4:5], v[76:77] op_sel:[0,1] op_sel_hi:[1,1]
	ds_read_b128 v[64:67], v20 offset:13056
	v_pk_fma_f32 v[22:23], v[6:7], v[38:39], v[22:23] op_sel:[0,0,0] op_sel_hi:[1,0,1]
	v_pk_fma_f32 v[26:27], v[6:7], v[78:79], v[26:27] op_sel:[0,0,0] op_sel_hi:[1,0,1]
	ds_read_b64 v[80:81], v21 offset:45824
	v_pk_fma_f32 v[22:23], v[8:9], v[38:39], v[22:23] op_sel:[0,1,0] op_sel_hi:[1,1,1]
	v_pk_fma_f32 v[84:85], v[8:9], v[78:79], v[84:85] op_sel:[0,1,0] op_sel_hi:[1,1,1]
	ds_read_b128 v[72:75], v20 offset:29440
	v_pk_add_f32 v[26:27], v[26:27], v[84:85]
	ds_read_b128 v[68:71], v20 offset:21248
	ds_read_b128 v[76:79], v20 offset:37632
	v_add_f32_dpp v28, v28, v28 row_ror:8 row_mask:0xf bank_mask:0x3
	v_add_f32_dpp v58, v58, v58 row_ror:8 row_mask:0xf bank_mask:0xc
	v_add_f32_dpp v22, v22, v22 quad_perm:[1,0,3,2] row_mask:0xf bank_mask:0xf
	v_add_f32_dpp v23, v23, v23 quad_perm:[1,0,3,2] row_mask:0xf bank_mask:0xf
	v_pk_mul_f32 v[84:85], v[2:3], v[40:41] op_sel:[0,0] op_sel_hi:[1,0]
	v_pk_mul_f32 v[86:87], v[4:5], v[40:41] op_sel:[0,1] op_sel_hi:[1,1]
	v_mov_b32_dpp v28, v58 quad_perm:[0,1,2,3] row_mask:0xf bank_mask:0xc
	v_add_f32_dpp v22, v22, v22 quad_perm:[2,3,0,1] row_mask:0xf bank_mask:0xf
	v_add_f32_dpp v23, v23, v23 quad_perm:[2,3,0,1] row_mask:0xf bank_mask:0xf
	v_pk_mul_f32 v[88:89], v[6:7], v[42:43] op_sel:[0,0] op_sel_hi:[1,0]
	v_pk_mul_f32 v[90:91], v[8:9], v[42:43] op_sel:[0,1] op_sel_hi:[1,1]
	v_add_f32_dpp v28, v28, v28 quad_perm:[1,0,3,2] row_mask:0xf bank_mask:0xf
	v_add_f32_dpp v22, v22, v22 row_half_mirror row_mask:0xf bank_mask:0xf
	v_add_f32_dpp v23, v23, v23 row_half_mirror row_mask:0xf bank_mask:0xf
	v_pk_fma_f32 v[84:85], v[48:49], v[56:57], v[84:85] op_sel:[0,0,0] op_sel_hi:[0,1,1]
	v_pk_fma_f32 v[86:87], v[48:49], v[56:57], v[86:87] op_sel:[1,0,0] op_sel_hi:[1,1,1]
	v_add_f32_dpp v28, v28, v28 quad_perm:[2,3,0,1] row_mask:0xf bank_mask:0xf
	v_add_f32_dpp v22, v22, v22 row_mirror row_mask:0xf bank_mask:0xf
	v_add_f32_dpp v23, v23, v23 row_mirror row_mask:0xf bank_mask:0xf
	v_pk_fma_f32 v[88:89], v[50:51], v[56:57], v[88:89] op_sel:[0,0,0] op_sel_hi:[0,1,1]
	v_pk_fma_f32 v[90:91], v[50:51], v[56:57], v[90:91] op_sel:[1,0,0] op_sel_hi:[1,1,1]
	v_cndmask_b32_e64 v31, v31, v28, s[10:11]
	v_pk_fma_f32 v[2:3], v[44:45], v[22:23], v[84:85] op_sel:[0,0,0] op_sel_hi:[0,1,1] neg_lo:[1,0,0] neg_hi:[1,0,0]
	v_pk_fma_f32 v[4:5], v[44:45], v[22:23], v[86:87] op_sel:[1,0,0] op_sel_hi:[1,1,1] neg_lo:[1,0,0] neg_hi:[1,0,0]
	v_pk_fma_f32 v[6:7], v[46:47], v[22:23], v[88:89] op_sel:[0,0,0] op_sel_hi:[0,1,1] neg_lo:[1,0,0] neg_hi:[1,0,0]
	v_pk_fma_f32 v[8:9], v[46:47], v[22:23], v[90:91] op_sel:[1,0,0] op_sel_hi:[1,1,1] neg_lo:[1,0,0] neg_hi:[1,0,0]
	s_waitcnt lgkmcnt(0)
	v_pk_mul_f32 v[22:23], v[2:3], v[60:61] op_sel:[0,0] op_sel_hi:[1,0]
	v_pk_mul_f32 v[28:29], v[2:3], v[52:53] op_sel:[0,0] op_sel_hi:[1,0]
	ds_read_b128 v[36:39], v20 offset:5120
	v_pk_fma_f32 v[22:23], v[4:5], v[60:61], v[22:23] op_sel:[0,1,0] op_sel_hi:[1,1,1]
	v_pk_mul_f32 v[84:85], v[4:5], v[52:53] op_sel:[0,1] op_sel_hi:[1,1]
	ds_read_b128 v[40:43], v20 offset:13312
	v_pk_fma_f32 v[22:23], v[6:7], v[62:63], v[22:23] op_sel:[0,0,0] op_sel_hi:[1,0,1]
	v_pk_fma_f32 v[28:29], v[6:7], v[54:55], v[28:29] op_sel:[0,0,0] op_sel_hi:[1,0,1]
	ds_read_b64 v[56:57], v21 offset:46080
	v_pk_fma_f32 v[22:23], v[8:9], v[62:63], v[22:23] op_sel:[0,1,0] op_sel_hi:[1,1,1]
	v_pk_fma_f32 v[84:85], v[8:9], v[54:55], v[84:85] op_sel:[0,1,0] op_sel_hi:[1,1,1]
	ds_read_b128 v[48:51], v20 offset:29696
	v_pk_add_f32 v[28:29], v[28:29], v[84:85]
	ds_read_b128 v[44:47], v20 offset:21504
	ds_read_b128 v[52:55], v20 offset:37888
	v_add_f32_dpp v24, v24, v24 row_ror:12 row_mask:0xf bank_mask:0x5
	v_add_f32_dpp v25, v25, v25 row_ror:4 row_mask:0xf bank_mask:0xa
	v_add_f32_dpp v22, v22, v22 quad_perm:[1,0,3,2] row_mask:0xf bank_mask:0xf
	v_add_f32_dpp v23, v23, v23 quad_perm:[1,0,3,2] row_mask:0xf bank_mask:0xf
	v_pk_mul_f32 v[84:85], v[2:3], v[64:65] op_sel:[0,0] op_sel_hi:[1,0]
	v_pk_mul_f32 v[86:87], v[4:5], v[64:65] op_sel:[0,1] op_sel_hi:[1,1]
	v_add_f32_dpp v26, v26, v26 row_ror:12 row_mask:0xf bank_mask:0x5
	v_add_f32_dpp v22, v22, v22 quad_perm:[2,3,0,1] row_mask:0xf bank_mask:0xf
	v_add_f32_dpp v23, v23, v23 quad_perm:[2,3,0,1] row_mask:0xf bank_mask:0xf
	v_pk_mul_f32 v[88:89], v[6:7], v[66:67] op_sel:[0,0] op_sel_hi:[1,0]
	v_pk_mul_f32 v[90:91], v[8:9], v[66:67] op_sel:[0,1] op_sel_hi:[1,1]
	v_add_f32_dpp v27, v27, v27 row_ror:4 row_mask:0xf bank_mask:0xa
	v_add_f32_dpp v22, v22, v22 row_half_mirror row_mask:0xf bank_mask:0xf
	v_add_f32_dpp v23, v23, v23 row_half_mirror row_mask:0xf bank_mask:0xf
	v_pk_fma_f32 v[84:85], v[72:73], v[80:81], v[84:85] op_sel:[0,0,0] op_sel_hi:[0,1,1]
	v_pk_fma_f32 v[86:87], v[72:73], v[80:81], v[86:87] op_sel:[1,0,0] op_sel_hi:[1,1,1]
	v_mov_b32_dpp v24, v25 quad_perm:[0,1,2,3] row_mask:0xf bank_mask:0xa
	v_add_f32_dpp v22, v22, v22 row_mirror row_mask:0xf bank_mask:0xf
	v_add_f32_dpp v23, v23, v23 row_mirror row_mask:0xf bank_mask:0xf
	v_pk_fma_f32 v[88:89], v[74:75], v[80:81], v[88:89] op_sel:[0,0,0] op_sel_hi:[0,1,1]
	v_pk_fma_f32 v[90:91], v[74:75], v[80:81], v[90:91] op_sel:[1,0,0] op_sel_hi:[1,1,1]
	v_mov_b32_dpp v26, v27 quad_perm:[0,1,2,3] row_mask:0xf bank_mask:0xa
	v_pk_fma_f32 v[2:3], v[68:69], v[22:23], v[84:85] op_sel:[0,0,0] op_sel_hi:[0,1,1] neg_lo:[1,0,0] neg_hi:[1,0,0]
	v_pk_fma_f32 v[4:5], v[68:69], v[22:23], v[86:87] op_sel:[1,0,0] op_sel_hi:[1,1,1] neg_lo:[1,0,0] neg_hi:[1,0,0]
	v_pk_fma_f32 v[6:7], v[70:71], v[22:23], v[88:89] op_sel:[0,0,0] op_sel_hi:[0,1,1] neg_lo:[1,0,0] neg_hi:[1,0,0]
	v_pk_fma_f32 v[8:9], v[70:71], v[22:23], v[90:91] op_sel:[1,0,0] op_sel_hi:[1,1,1] neg_lo:[1,0,0] neg_hi:[1,0,0]
	s_waitcnt lgkmcnt(0)
	v_pk_mul_f32 v[22:23], v[2:3], v[36:37] op_sel:[0,0] op_sel_hi:[1,0]
	v_pk_mul_f32 v[58:59], v[2:3], v[76:77] op_sel:[0,0] op_sel_hi:[1,0]
	ds_read_b128 v[60:63], v20 offset:5376
	v_pk_fma_f32 v[22:23], v[4:5], v[36:37], v[22:23] op_sel:[0,1,0] op_sel_hi:[1,1,1]
	v_pk_mul_f32 v[84:85], v[4:5], v[76:77] op_sel:[0,1] op_sel_hi:[1,1]
	ds_read_b128 v[64:67], v20 offset:13568
	v_pk_fma_f32 v[22:23], v[6:7], v[38:39], v[22:23] op_sel:[0,0,0] op_sel_hi:[1,0,1]
	v_pk_fma_f32 v[58:59], v[6:7], v[78:79], v[58:59] op_sel:[0,0,0] op_sel_hi:[1,0,1]
	ds_read_b64 v[80:81], v21 offset:46336
	v_pk_fma_f32 v[22:23], v[8:9], v[38:39], v[22:23] op_sel:[0,1,0] op_sel_hi:[1,1,1]
	v_pk_fma_f32 v[84:85], v[8:9], v[78:79], v[84:85] op_sel:[0,1,0] op_sel_hi:[1,1,1]
	ds_read_b128 v[72:75], v20 offset:29952
	v_pk_add_f32 v[58:59], v[58:59], v[84:85]
	ds_read_b128 v[68:71], v20 offset:21760
	ds_read_b128 v[76:79], v20 offset:38144
	v_add_f32_dpp v24, v24, v24 row_ror:8 row_mask:0xf bank_mask:0x3
	v_add_f32_dpp v26, v26, v26 row_ror:8 row_mask:0xf bank_mask:0xc
	v_add_f32_dpp v22, v22, v22 quad_perm:[1,0,3,2] row_mask:0xf bank_mask:0xf
	v_add_f32_dpp v23, v23, v23 quad_perm:[1,0,3,2] row_mask:0xf bank_mask:0xf
	v_pk_mul_f32 v[84:85], v[2:3], v[40:41] op_sel:[0,0] op_sel_hi:[1,0]
	v_pk_mul_f32 v[86:87], v[4:5], v[40:41] op_sel:[0,1] op_sel_hi:[1,1]
	v_mov_b32_dpp v24, v26 quad_perm:[0,1,2,3] row_mask:0xf bank_mask:0xc
	v_add_f32_dpp v22, v22, v22 quad_perm:[2,3,0,1] row_mask:0xf bank_mask:0xf
	v_add_f32_dpp v23, v23, v23 quad_perm:[2,3,0,1] row_mask:0xf bank_mask:0xf
	v_pk_mul_f32 v[88:89], v[6:7], v[42:43] op_sel:[0,0] op_sel_hi:[1,0]
	v_pk_mul_f32 v[90:91], v[8:9], v[42:43] op_sel:[0,1] op_sel_hi:[1,1]
	v_add_f32_dpp v24, v24, v24 quad_perm:[1,0,3,2] row_mask:0xf bank_mask:0xf
	v_add_f32_dpp v22, v22, v22 row_half_mirror row_mask:0xf bank_mask:0xf
	v_add_f32_dpp v23, v23, v23 row_half_mirror row_mask:0xf bank_mask:0xf
	v_pk_fma_f32 v[84:85], v[48:49], v[56:57], v[84:85] op_sel:[0,0,0] op_sel_hi:[0,1,1]
	v_pk_fma_f32 v[86:87], v[48:49], v[56:57], v[86:87] op_sel:[1,0,0] op_sel_hi:[1,1,1]
	v_add_f32_dpp v24, v24, v24 quad_perm:[2,3,0,1] row_mask:0xf bank_mask:0xf
	v_add_f32_dpp v22, v22, v22 row_mirror row_mask:0xf bank_mask:0xf
	v_add_f32_dpp v23, v23, v23 row_mirror row_mask:0xf bank_mask:0xf
	v_pk_fma_f32 v[88:89], v[50:51], v[56:57], v[88:89] op_sel:[0,0,0] op_sel_hi:[0,1,1]
	v_pk_fma_f32 v[90:91], v[50:51], v[56:57], v[90:91] op_sel:[1,0,0] op_sel_hi:[1,1,1]
	v_cndmask_b32_e64 v32, 0, v24, s[0:1]
	v_pk_fma_f32 v[2:3], v[44:45], v[22:23], v[84:85] op_sel:[0,0,0] op_sel_hi:[0,1,1] neg_lo:[1,0,0] neg_hi:[1,0,0]
	v_pk_fma_f32 v[4:5], v[44:45], v[22:23], v[86:87] op_sel:[1,0,0] op_sel_hi:[1,1,1] neg_lo:[1,0,0] neg_hi:[1,0,0]
	v_pk_fma_f32 v[6:7], v[46:47], v[22:23], v[88:89] op_sel:[0,0,0] op_sel_hi:[0,1,1] neg_lo:[1,0,0] neg_hi:[1,0,0]
	v_pk_fma_f32 v[8:9], v[46:47], v[22:23], v[90:91] op_sel:[1,0,0] op_sel_hi:[1,1,1] neg_lo:[1,0,0] neg_hi:[1,0,0]
	s_waitcnt lgkmcnt(0)
	v_pk_mul_f32 v[22:23], v[2:3], v[60:61] op_sel:[0,0] op_sel_hi:[1,0]
	v_pk_mul_f32 v[24:25], v[2:3], v[52:53] op_sel:[0,0] op_sel_hi:[1,0]
	ds_read_b128 v[36:39], v20 offset:5632
	v_pk_fma_f32 v[22:23], v[4:5], v[60:61], v[22:23] op_sel:[0,1,0] op_sel_hi:[1,1,1]
	v_pk_mul_f32 v[84:85], v[4:5], v[52:53] op_sel:[0,1] op_sel_hi:[1,1]
	ds_read_b128 v[40:43], v20 offset:13824
	v_pk_fma_f32 v[22:23], v[6:7], v[62:63], v[22:23] op_sel:[0,0,0] op_sel_hi:[1,0,1]
	v_pk_fma_f32 v[24:25], v[6:7], v[54:55], v[24:25] op_sel:[0,0,0] op_sel_hi:[1,0,1]
	ds_read_b64 v[56:57], v21 offset:46592
	v_pk_fma_f32 v[22:23], v[8:9], v[62:63], v[22:23] op_sel:[0,1,0] op_sel_hi:[1,1,1]
	v_pk_fma_f32 v[84:85], v[8:9], v[54:55], v[84:85] op_sel:[0,1,0] op_sel_hi:[1,1,1]
	ds_read_b128 v[48:51], v20 offset:30208
	v_pk_add_f32 v[24:25], v[24:25], v[84:85]
	ds_read_b128 v[44:47], v20 offset:22016
	ds_read_b128 v[52:55], v20 offset:38400
	v_add_f32_dpp v28, v28, v28 row_ror:12 row_mask:0xf bank_mask:0x5
	v_add_f32_dpp v29, v29, v29 row_ror:4 row_mask:0xf bank_mask:0xa
	v_add_f32_dpp v22, v22, v22 quad_perm:[1,0,3,2] row_mask:0xf bank_mask:0xf
	v_add_f32_dpp v23, v23, v23 quad_perm:[1,0,3,2] row_mask:0xf bank_mask:0xf
	v_pk_mul_f32 v[84:85], v[2:3], v[64:65] op_sel:[0,0] op_sel_hi:[1,0]
	v_pk_mul_f32 v[86:87], v[4:5], v[64:65] op_sel:[0,1] op_sel_hi:[1,1]
	v_add_f32_dpp v58, v58, v58 row_ror:12 row_mask:0xf bank_mask:0x5
	v_add_f32_dpp v22, v22, v22 quad_perm:[2,3,0,1] row_mask:0xf bank_mask:0xf
	v_add_f32_dpp v23, v23, v23 quad_perm:[2,3,0,1] row_mask:0xf bank_mask:0xf
	v_pk_mul_f32 v[88:89], v[6:7], v[66:67] op_sel:[0,0] op_sel_hi:[1,0]
	v_pk_mul_f32 v[90:91], v[8:9], v[66:67] op_sel:[0,1] op_sel_hi:[1,1]
	v_add_f32_dpp v59, v59, v59 row_ror:4 row_mask:0xf bank_mask:0xa
	v_add_f32_dpp v22, v22, v22 row_half_mirror row_mask:0xf bank_mask:0xf
	v_add_f32_dpp v23, v23, v23 row_half_mirror row_mask:0xf bank_mask:0xf
	v_pk_fma_f32 v[84:85], v[72:73], v[80:81], v[84:85] op_sel:[0,0,0] op_sel_hi:[0,1,1]
	v_pk_fma_f32 v[86:87], v[72:73], v[80:81], v[86:87] op_sel:[1,0,0] op_sel_hi:[1,1,1]
	v_mov_b32_dpp v28, v29 quad_perm:[0,1,2,3] row_mask:0xf bank_mask:0xa
	v_add_f32_dpp v22, v22, v22 row_mirror row_mask:0xf bank_mask:0xf
	v_add_f32_dpp v23, v23, v23 row_mirror row_mask:0xf bank_mask:0xf
	v_pk_fma_f32 v[88:89], v[74:75], v[80:81], v[88:89] op_sel:[0,0,0] op_sel_hi:[0,1,1]
	v_pk_fma_f32 v[90:91], v[74:75], v[80:81], v[90:91] op_sel:[1,0,0] op_sel_hi:[1,1,1]
	v_mov_b32_dpp v58, v59 quad_perm:[0,1,2,3] row_mask:0xf bank_mask:0xa
	v_pk_fma_f32 v[2:3], v[68:69], v[22:23], v[84:85] op_sel:[0,0,0] op_sel_hi:[0,1,1] neg_lo:[1,0,0] neg_hi:[1,0,0]
	v_pk_fma_f32 v[4:5], v[68:69], v[22:23], v[86:87] op_sel:[1,0,0] op_sel_hi:[1,1,1] neg_lo:[1,0,0] neg_hi:[1,0,0]
	v_pk_fma_f32 v[6:7], v[70:71], v[22:23], v[88:89] op_sel:[0,0,0] op_sel_hi:[0,1,1] neg_lo:[1,0,0] neg_hi:[1,0,0]
	v_pk_fma_f32 v[8:9], v[70:71], v[22:23], v[90:91] op_sel:[1,0,0] op_sel_hi:[1,1,1] neg_lo:[1,0,0] neg_hi:[1,0,0]
	s_waitcnt lgkmcnt(0)
	v_pk_mul_f32 v[22:23], v[2:3], v[36:37] op_sel:[0,0] op_sel_hi:[1,0]
	v_pk_mul_f32 v[26:27], v[2:3], v[76:77] op_sel:[0,0] op_sel_hi:[1,0]
	ds_read_b128 v[60:63], v20 offset:5888
	v_pk_fma_f32 v[22:23], v[4:5], v[36:37], v[22:23] op_sel:[0,1,0] op_sel_hi:[1,1,1]
	v_pk_mul_f32 v[84:85], v[4:5], v[76:77] op_sel:[0,1] op_sel_hi:[1,1]
	ds_read_b128 v[64:67], v20 offset:14080
	v_pk_fma_f32 v[22:23], v[6:7], v[38:39], v[22:23] op_sel:[0,0,0] op_sel_hi:[1,0,1]
	v_pk_fma_f32 v[26:27], v[6:7], v[78:79], v[26:27] op_sel:[0,0,0] op_sel_hi:[1,0,1]
	ds_read_b64 v[80:81], v21 offset:46848
	v_pk_fma_f32 v[22:23], v[8:9], v[38:39], v[22:23] op_sel:[0,1,0] op_sel_hi:[1,1,1]
	v_pk_fma_f32 v[84:85], v[8:9], v[78:79], v[84:85] op_sel:[0,1,0] op_sel_hi:[1,1,1]
	ds_read_b128 v[72:75], v20 offset:30464
	v_pk_add_f32 v[26:27], v[26:27], v[84:85]
	ds_read_b128 v[68:71], v20 offset:22272
	ds_read_b128 v[76:79], v20 offset:38656
	v_add_f32_dpp v28, v28, v28 row_ror:8 row_mask:0xf bank_mask:0x3
	v_add_f32_dpp v58, v58, v58 row_ror:8 row_mask:0xf bank_mask:0xc
	v_add_f32_dpp v22, v22, v22 quad_perm:[1,0,3,2] row_mask:0xf bank_mask:0xf
	v_add_f32_dpp v23, v23, v23 quad_perm:[1,0,3,2] row_mask:0xf bank_mask:0xf
	v_pk_mul_f32 v[84:85], v[2:3], v[40:41] op_sel:[0,0] op_sel_hi:[1,0]
	v_pk_mul_f32 v[86:87], v[4:5], v[40:41] op_sel:[0,1] op_sel_hi:[1,1]
	v_mov_b32_dpp v28, v58 quad_perm:[0,1,2,3] row_mask:0xf bank_mask:0xc
	v_add_f32_dpp v22, v22, v22 quad_perm:[2,3,0,1] row_mask:0xf bank_mask:0xf
	v_add_f32_dpp v23, v23, v23 quad_perm:[2,3,0,1] row_mask:0xf bank_mask:0xf
	v_pk_mul_f32 v[88:89], v[6:7], v[42:43] op_sel:[0,0] op_sel_hi:[1,0]
	v_pk_mul_f32 v[90:91], v[8:9], v[42:43] op_sel:[0,1] op_sel_hi:[1,1]
	v_add_f32_dpp v28, v28, v28 quad_perm:[1,0,3,2] row_mask:0xf bank_mask:0xf
	v_add_f32_dpp v22, v22, v22 row_half_mirror row_mask:0xf bank_mask:0xf
	v_add_f32_dpp v23, v23, v23 row_half_mirror row_mask:0xf bank_mask:0xf
	v_pk_fma_f32 v[84:85], v[48:49], v[56:57], v[84:85] op_sel:[0,0,0] op_sel_hi:[0,1,1]
	v_pk_fma_f32 v[86:87], v[48:49], v[56:57], v[86:87] op_sel:[1,0,0] op_sel_hi:[1,1,1]
	v_add_f32_dpp v28, v28, v28 quad_perm:[2,3,0,1] row_mask:0xf bank_mask:0xf
	v_add_f32_dpp v22, v22, v22 row_mirror row_mask:0xf bank_mask:0xf
	v_add_f32_dpp v23, v23, v23 row_mirror row_mask:0xf bank_mask:0xf
	v_pk_fma_f32 v[88:89], v[50:51], v[56:57], v[88:89] op_sel:[0,0,0] op_sel_hi:[0,1,1]
	v_pk_fma_f32 v[90:91], v[50:51], v[56:57], v[90:91] op_sel:[1,0,0] op_sel_hi:[1,1,1]
	v_cndmask_b32_e64 v32, v32, v28, s[6:7]
	v_pk_fma_f32 v[2:3], v[44:45], v[22:23], v[84:85] op_sel:[0,0,0] op_sel_hi:[0,1,1] neg_lo:[1,0,0] neg_hi:[1,0,0]
	v_pk_fma_f32 v[4:5], v[44:45], v[22:23], v[86:87] op_sel:[1,0,0] op_sel_hi:[1,1,1] neg_lo:[1,0,0] neg_hi:[1,0,0]
	v_pk_fma_f32 v[6:7], v[46:47], v[22:23], v[88:89] op_sel:[0,0,0] op_sel_hi:[0,1,1] neg_lo:[1,0,0] neg_hi:[1,0,0]
	v_pk_fma_f32 v[8:9], v[46:47], v[22:23], v[90:91] op_sel:[1,0,0] op_sel_hi:[1,1,1] neg_lo:[1,0,0] neg_hi:[1,0,0]
	s_waitcnt lgkmcnt(0)
	v_pk_mul_f32 v[22:23], v[2:3], v[60:61] op_sel:[0,0] op_sel_hi:[1,0]
	v_pk_mul_f32 v[28:29], v[2:3], v[52:53] op_sel:[0,0] op_sel_hi:[1,0]
	ds_read_b128 v[36:39], v20 offset:6144
	v_pk_fma_f32 v[22:23], v[4:5], v[60:61], v[22:23] op_sel:[0,1,0] op_sel_hi:[1,1,1]
	v_pk_mul_f32 v[84:85], v[4:5], v[52:53] op_sel:[0,1] op_sel_hi:[1,1]
	ds_read_b128 v[40:43], v20 offset:14336
	v_pk_fma_f32 v[22:23], v[6:7], v[62:63], v[22:23] op_sel:[0,0,0] op_sel_hi:[1,0,1]
	v_pk_fma_f32 v[28:29], v[6:7], v[54:55], v[28:29] op_sel:[0,0,0] op_sel_hi:[1,0,1]
	ds_read_b64 v[56:57], v21 offset:47104
	v_pk_fma_f32 v[22:23], v[8:9], v[62:63], v[22:23] op_sel:[0,1,0] op_sel_hi:[1,1,1]
	v_pk_fma_f32 v[84:85], v[8:9], v[54:55], v[84:85] op_sel:[0,1,0] op_sel_hi:[1,1,1]
	ds_read_b128 v[48:51], v20 offset:30720
	v_pk_add_f32 v[28:29], v[28:29], v[84:85]
	ds_read_b128 v[44:47], v20 offset:22528
	ds_read_b128 v[52:55], v20 offset:38912
	v_add_f32_dpp v24, v24, v24 row_ror:12 row_mask:0xf bank_mask:0x5
	v_add_f32_dpp v25, v25, v25 row_ror:4 row_mask:0xf bank_mask:0xa
	v_add_f32_dpp v22, v22, v22 quad_perm:[1,0,3,2] row_mask:0xf bank_mask:0xf
	v_add_f32_dpp v23, v23, v23 quad_perm:[1,0,3,2] row_mask:0xf bank_mask:0xf
	v_pk_mul_f32 v[84:85], v[2:3], v[64:65] op_sel:[0,0] op_sel_hi:[1,0]
	v_pk_mul_f32 v[86:87], v[4:5], v[64:65] op_sel:[0,1] op_sel_hi:[1,1]
	v_add_f32_dpp v26, v26, v26 row_ror:12 row_mask:0xf bank_mask:0x5
	v_add_f32_dpp v22, v22, v22 quad_perm:[2,3,0,1] row_mask:0xf bank_mask:0xf
	v_add_f32_dpp v23, v23, v23 quad_perm:[2,3,0,1] row_mask:0xf bank_mask:0xf
	v_pk_mul_f32 v[88:89], v[6:7], v[66:67] op_sel:[0,0] op_sel_hi:[1,0]
	v_pk_mul_f32 v[90:91], v[8:9], v[66:67] op_sel:[0,1] op_sel_hi:[1,1]
	v_add_f32_dpp v27, v27, v27 row_ror:4 row_mask:0xf bank_mask:0xa
	v_add_f32_dpp v22, v22, v22 row_half_mirror row_mask:0xf bank_mask:0xf
	v_add_f32_dpp v23, v23, v23 row_half_mirror row_mask:0xf bank_mask:0xf
	v_pk_fma_f32 v[84:85], v[72:73], v[80:81], v[84:85] op_sel:[0,0,0] op_sel_hi:[0,1,1]
	v_pk_fma_f32 v[86:87], v[72:73], v[80:81], v[86:87] op_sel:[1,0,0] op_sel_hi:[1,1,1]
	v_mov_b32_dpp v24, v25 quad_perm:[0,1,2,3] row_mask:0xf bank_mask:0xa
	v_add_f32_dpp v22, v22, v22 row_mirror row_mask:0xf bank_mask:0xf
	v_add_f32_dpp v23, v23, v23 row_mirror row_mask:0xf bank_mask:0xf
	v_pk_fma_f32 v[88:89], v[74:75], v[80:81], v[88:89] op_sel:[0,0,0] op_sel_hi:[0,1,1]
	v_pk_fma_f32 v[90:91], v[74:75], v[80:81], v[90:91] op_sel:[1,0,0] op_sel_hi:[1,1,1]
	v_mov_b32_dpp v26, v27 quad_perm:[0,1,2,3] row_mask:0xf bank_mask:0xa
	v_pk_fma_f32 v[2:3], v[68:69], v[22:23], v[84:85] op_sel:[0,0,0] op_sel_hi:[0,1,1] neg_lo:[1,0,0] neg_hi:[1,0,0]
	v_pk_fma_f32 v[4:5], v[68:69], v[22:23], v[86:87] op_sel:[1,0,0] op_sel_hi:[1,1,1] neg_lo:[1,0,0] neg_hi:[1,0,0]
	v_pk_fma_f32 v[6:7], v[70:71], v[22:23], v[88:89] op_sel:[0,0,0] op_sel_hi:[0,1,1] neg_lo:[1,0,0] neg_hi:[1,0,0]
	v_pk_fma_f32 v[8:9], v[70:71], v[22:23], v[90:91] op_sel:[1,0,0] op_sel_hi:[1,1,1] neg_lo:[1,0,0] neg_hi:[1,0,0]
	s_waitcnt lgkmcnt(0)
	v_pk_mul_f32 v[22:23], v[2:3], v[36:37] op_sel:[0,0] op_sel_hi:[1,0]
	v_pk_mul_f32 v[58:59], v[2:3], v[76:77] op_sel:[0,0] op_sel_hi:[1,0]
	ds_read_b128 v[60:63], v20 offset:6400
	v_pk_fma_f32 v[22:23], v[4:5], v[36:37], v[22:23] op_sel:[0,1,0] op_sel_hi:[1,1,1]
	v_pk_mul_f32 v[84:85], v[4:5], v[76:77] op_sel:[0,1] op_sel_hi:[1,1]
	ds_read_b128 v[64:67], v20 offset:14592
	v_pk_fma_f32 v[22:23], v[6:7], v[38:39], v[22:23] op_sel:[0,0,0] op_sel_hi:[1,0,1]
	v_pk_fma_f32 v[58:59], v[6:7], v[78:79], v[58:59] op_sel:[0,0,0] op_sel_hi:[1,0,1]
	ds_read_b64 v[80:81], v21 offset:47360
	v_pk_fma_f32 v[22:23], v[8:9], v[38:39], v[22:23] op_sel:[0,1,0] op_sel_hi:[1,1,1]
	v_pk_fma_f32 v[84:85], v[8:9], v[78:79], v[84:85] op_sel:[0,1,0] op_sel_hi:[1,1,1]
	ds_read_b128 v[72:75], v20 offset:30976
	v_pk_add_f32 v[58:59], v[58:59], v[84:85]
	ds_read_b128 v[68:71], v20 offset:22784
	ds_read_b128 v[76:79], v20 offset:39168
	v_add_f32_dpp v24, v24, v24 row_ror:8 row_mask:0xf bank_mask:0x3
	v_add_f32_dpp v26, v26, v26 row_ror:8 row_mask:0xf bank_mask:0xc
	v_add_f32_dpp v22, v22, v22 quad_perm:[1,0,3,2] row_mask:0xf bank_mask:0xf
	v_add_f32_dpp v23, v23, v23 quad_perm:[1,0,3,2] row_mask:0xf bank_mask:0xf
	v_pk_mul_f32 v[84:85], v[2:3], v[40:41] op_sel:[0,0] op_sel_hi:[1,0]
	v_pk_mul_f32 v[86:87], v[4:5], v[40:41] op_sel:[0,1] op_sel_hi:[1,1]
	v_mov_b32_dpp v24, v26 quad_perm:[0,1,2,3] row_mask:0xf bank_mask:0xc
	v_add_f32_dpp v22, v22, v22 quad_perm:[2,3,0,1] row_mask:0xf bank_mask:0xf
	v_add_f32_dpp v23, v23, v23 quad_perm:[2,3,0,1] row_mask:0xf bank_mask:0xf
	v_pk_mul_f32 v[88:89], v[6:7], v[42:43] op_sel:[0,0] op_sel_hi:[1,0]
	v_pk_mul_f32 v[90:91], v[8:9], v[42:43] op_sel:[0,1] op_sel_hi:[1,1]
	v_add_f32_dpp v24, v24, v24 quad_perm:[1,0,3,2] row_mask:0xf bank_mask:0xf
	v_add_f32_dpp v22, v22, v22 row_half_mirror row_mask:0xf bank_mask:0xf
	v_add_f32_dpp v23, v23, v23 row_half_mirror row_mask:0xf bank_mask:0xf
	v_pk_fma_f32 v[84:85], v[48:49], v[56:57], v[84:85] op_sel:[0,0,0] op_sel_hi:[0,1,1]
	v_pk_fma_f32 v[86:87], v[48:49], v[56:57], v[86:87] op_sel:[1,0,0] op_sel_hi:[1,1,1]
	v_add_f32_dpp v24, v24, v24 quad_perm:[2,3,0,1] row_mask:0xf bank_mask:0xf
	v_add_f32_dpp v22, v22, v22 row_mirror row_mask:0xf bank_mask:0xf
	v_add_f32_dpp v23, v23, v23 row_mirror row_mask:0xf bank_mask:0xf
	v_pk_fma_f32 v[88:89], v[50:51], v[56:57], v[88:89] op_sel:[0,0,0] op_sel_hi:[0,1,1]
	v_pk_fma_f32 v[90:91], v[50:51], v[56:57], v[90:91] op_sel:[1,0,0] op_sel_hi:[1,1,1]
	v_cndmask_b32_e64 v32, v32, v24, s[8:9]
	v_pk_fma_f32 v[2:3], v[44:45], v[22:23], v[84:85] op_sel:[0,0,0] op_sel_hi:[0,1,1] neg_lo:[1,0,0] neg_hi:[1,0,0]
	v_pk_fma_f32 v[4:5], v[44:45], v[22:23], v[86:87] op_sel:[1,0,0] op_sel_hi:[1,1,1] neg_lo:[1,0,0] neg_hi:[1,0,0]
	v_pk_fma_f32 v[6:7], v[46:47], v[22:23], v[88:89] op_sel:[0,0,0] op_sel_hi:[0,1,1] neg_lo:[1,0,0] neg_hi:[1,0,0]
	v_pk_fma_f32 v[8:9], v[46:47], v[22:23], v[90:91] op_sel:[1,0,0] op_sel_hi:[1,1,1] neg_lo:[1,0,0] neg_hi:[1,0,0]
	s_waitcnt lgkmcnt(0)
	v_pk_mul_f32 v[22:23], v[2:3], v[60:61] op_sel:[0,0] op_sel_hi:[1,0]
	v_pk_mul_f32 v[24:25], v[2:3], v[52:53] op_sel:[0,0] op_sel_hi:[1,0]
	ds_read_b128 v[36:39], v20 offset:6656
	v_pk_fma_f32 v[22:23], v[4:5], v[60:61], v[22:23] op_sel:[0,1,0] op_sel_hi:[1,1,1]
	v_pk_mul_f32 v[84:85], v[4:5], v[52:53] op_sel:[0,1] op_sel_hi:[1,1]
	ds_read_b128 v[40:43], v20 offset:14848
	v_pk_fma_f32 v[22:23], v[6:7], v[62:63], v[22:23] op_sel:[0,0,0] op_sel_hi:[1,0,1]
	v_pk_fma_f32 v[24:25], v[6:7], v[54:55], v[24:25] op_sel:[0,0,0] op_sel_hi:[1,0,1]
	ds_read_b64 v[56:57], v21 offset:47616
	v_pk_fma_f32 v[22:23], v[8:9], v[62:63], v[22:23] op_sel:[0,1,0] op_sel_hi:[1,1,1]
	v_pk_fma_f32 v[84:85], v[8:9], v[54:55], v[84:85] op_sel:[0,1,0] op_sel_hi:[1,1,1]
	ds_read_b128 v[48:51], v20 offset:31232
	v_pk_add_f32 v[24:25], v[24:25], v[84:85]
	ds_read_b128 v[44:47], v20 offset:23040
	ds_read_b128 v[52:55], v20 offset:39424
	v_add_f32_dpp v28, v28, v28 row_ror:12 row_mask:0xf bank_mask:0x5
	v_add_f32_dpp v29, v29, v29 row_ror:4 row_mask:0xf bank_mask:0xa
	v_add_f32_dpp v22, v22, v22 quad_perm:[1,0,3,2] row_mask:0xf bank_mask:0xf
	v_add_f32_dpp v23, v23, v23 quad_perm:[1,0,3,2] row_mask:0xf bank_mask:0xf
	v_pk_mul_f32 v[84:85], v[2:3], v[64:65] op_sel:[0,0] op_sel_hi:[1,0]
	v_pk_mul_f32 v[86:87], v[4:5], v[64:65] op_sel:[0,1] op_sel_hi:[1,1]
	v_add_f32_dpp v58, v58, v58 row_ror:12 row_mask:0xf bank_mask:0x5
	v_add_f32_dpp v22, v22, v22 quad_perm:[2,3,0,1] row_mask:0xf bank_mask:0xf
	v_add_f32_dpp v23, v23, v23 quad_perm:[2,3,0,1] row_mask:0xf bank_mask:0xf
	v_pk_mul_f32 v[88:89], v[6:7], v[66:67] op_sel:[0,0] op_sel_hi:[1,0]
	v_pk_mul_f32 v[90:91], v[8:9], v[66:67] op_sel:[0,1] op_sel_hi:[1,1]
	v_add_f32_dpp v59, v59, v59 row_ror:4 row_mask:0xf bank_mask:0xa
	v_add_f32_dpp v22, v22, v22 row_half_mirror row_mask:0xf bank_mask:0xf
	v_add_f32_dpp v23, v23, v23 row_half_mirror row_mask:0xf bank_mask:0xf
	v_pk_fma_f32 v[84:85], v[72:73], v[80:81], v[84:85] op_sel:[0,0,0] op_sel_hi:[0,1,1]
	v_pk_fma_f32 v[86:87], v[72:73], v[80:81], v[86:87] op_sel:[1,0,0] op_sel_hi:[1,1,1]
	v_mov_b32_dpp v28, v29 quad_perm:[0,1,2,3] row_mask:0xf bank_mask:0xa
	v_add_f32_dpp v22, v22, v22 row_mirror row_mask:0xf bank_mask:0xf
	v_add_f32_dpp v23, v23, v23 row_mirror row_mask:0xf bank_mask:0xf
	v_pk_fma_f32 v[88:89], v[74:75], v[80:81], v[88:89] op_sel:[0,0,0] op_sel_hi:[0,1,1]
	v_pk_fma_f32 v[90:91], v[74:75], v[80:81], v[90:91] op_sel:[1,0,0] op_sel_hi:[1,1,1]
	v_mov_b32_dpp v58, v59 quad_perm:[0,1,2,3] row_mask:0xf bank_mask:0xa
	v_pk_fma_f32 v[2:3], v[68:69], v[22:23], v[84:85] op_sel:[0,0,0] op_sel_hi:[0,1,1] neg_lo:[1,0,0] neg_hi:[1,0,0]
	v_pk_fma_f32 v[4:5], v[68:69], v[22:23], v[86:87] op_sel:[1,0,0] op_sel_hi:[1,1,1] neg_lo:[1,0,0] neg_hi:[1,0,0]
	v_pk_fma_f32 v[6:7], v[70:71], v[22:23], v[88:89] op_sel:[0,0,0] op_sel_hi:[0,1,1] neg_lo:[1,0,0] neg_hi:[1,0,0]
	v_pk_fma_f32 v[8:9], v[70:71], v[22:23], v[90:91] op_sel:[1,0,0] op_sel_hi:[1,1,1] neg_lo:[1,0,0] neg_hi:[1,0,0]
	s_waitcnt lgkmcnt(0)
	v_pk_mul_f32 v[22:23], v[2:3], v[36:37] op_sel:[0,0] op_sel_hi:[1,0]
	v_pk_mul_f32 v[26:27], v[2:3], v[76:77] op_sel:[0,0] op_sel_hi:[1,0]
	ds_read_b128 v[60:63], v20 offset:6912
	v_pk_fma_f32 v[22:23], v[4:5], v[36:37], v[22:23] op_sel:[0,1,0] op_sel_hi:[1,1,1]
	v_pk_mul_f32 v[84:85], v[4:5], v[76:77] op_sel:[0,1] op_sel_hi:[1,1]
	ds_read_b128 v[64:67], v20 offset:15104
	v_pk_fma_f32 v[22:23], v[6:7], v[38:39], v[22:23] op_sel:[0,0,0] op_sel_hi:[1,0,1]
	v_pk_fma_f32 v[26:27], v[6:7], v[78:79], v[26:27] op_sel:[0,0,0] op_sel_hi:[1,0,1]
	ds_read_b64 v[80:81], v21 offset:47872
	v_pk_fma_f32 v[22:23], v[8:9], v[38:39], v[22:23] op_sel:[0,1,0] op_sel_hi:[1,1,1]
	v_pk_fma_f32 v[84:85], v[8:9], v[78:79], v[84:85] op_sel:[0,1,0] op_sel_hi:[1,1,1]
	ds_read_b128 v[72:75], v20 offset:31488
	v_pk_add_f32 v[26:27], v[26:27], v[84:85]
	ds_read_b128 v[68:71], v20 offset:23296
	ds_read_b128 v[76:79], v20 offset:39680
	v_add_f32_dpp v28, v28, v28 row_ror:8 row_mask:0xf bank_mask:0x3
	v_add_f32_dpp v58, v58, v58 row_ror:8 row_mask:0xf bank_mask:0xc
	v_add_f32_dpp v22, v22, v22 quad_perm:[1,0,3,2] row_mask:0xf bank_mask:0xf
	v_add_f32_dpp v23, v23, v23 quad_perm:[1,0,3,2] row_mask:0xf bank_mask:0xf
	v_pk_mul_f32 v[84:85], v[2:3], v[40:41] op_sel:[0,0] op_sel_hi:[1,0]
	v_pk_mul_f32 v[86:87], v[4:5], v[40:41] op_sel:[0,1] op_sel_hi:[1,1]
	v_mov_b32_dpp v28, v58 quad_perm:[0,1,2,3] row_mask:0xf bank_mask:0xc
	v_add_f32_dpp v22, v22, v22 quad_perm:[2,3,0,1] row_mask:0xf bank_mask:0xf
	v_add_f32_dpp v23, v23, v23 quad_perm:[2,3,0,1] row_mask:0xf bank_mask:0xf
	v_pk_mul_f32 v[88:89], v[6:7], v[42:43] op_sel:[0,0] op_sel_hi:[1,0]
	v_pk_mul_f32 v[90:91], v[8:9], v[42:43] op_sel:[0,1] op_sel_hi:[1,1]
	v_add_f32_dpp v28, v28, v28 quad_perm:[1,0,3,2] row_mask:0xf bank_mask:0xf
	v_add_f32_dpp v22, v22, v22 row_half_mirror row_mask:0xf bank_mask:0xf
	v_add_f32_dpp v23, v23, v23 row_half_mirror row_mask:0xf bank_mask:0xf
	v_pk_fma_f32 v[84:85], v[48:49], v[56:57], v[84:85] op_sel:[0,0,0] op_sel_hi:[0,1,1]
	v_pk_fma_f32 v[86:87], v[48:49], v[56:57], v[86:87] op_sel:[1,0,0] op_sel_hi:[1,1,1]
	v_add_f32_dpp v28, v28, v28 quad_perm:[2,3,0,1] row_mask:0xf bank_mask:0xf
	v_add_f32_dpp v22, v22, v22 row_mirror row_mask:0xf bank_mask:0xf
	v_add_f32_dpp v23, v23, v23 row_mirror row_mask:0xf bank_mask:0xf
	v_pk_fma_f32 v[88:89], v[50:51], v[56:57], v[88:89] op_sel:[0,0,0] op_sel_hi:[0,1,1]
	v_pk_fma_f32 v[90:91], v[50:51], v[56:57], v[90:91] op_sel:[1,0,0] op_sel_hi:[1,1,1]
	v_cndmask_b32_e64 v32, v32, v28, s[10:11]
	v_pk_fma_f32 v[2:3], v[44:45], v[22:23], v[84:85] op_sel:[0,0,0] op_sel_hi:[0,1,1] neg_lo:[1,0,0] neg_hi:[1,0,0]
	v_pk_fma_f32 v[4:5], v[44:45], v[22:23], v[86:87] op_sel:[1,0,0] op_sel_hi:[1,1,1] neg_lo:[1,0,0] neg_hi:[1,0,0]
	v_pk_fma_f32 v[6:7], v[46:47], v[22:23], v[88:89] op_sel:[0,0,0] op_sel_hi:[0,1,1] neg_lo:[1,0,0] neg_hi:[1,0,0]
	v_pk_fma_f32 v[8:9], v[46:47], v[22:23], v[90:91] op_sel:[1,0,0] op_sel_hi:[1,1,1] neg_lo:[1,0,0] neg_hi:[1,0,0]
	s_waitcnt lgkmcnt(0)
	v_pk_mul_f32 v[22:23], v[2:3], v[60:61] op_sel:[0,0] op_sel_hi:[1,0]
	v_pk_mul_f32 v[28:29], v[2:3], v[52:53] op_sel:[0,0] op_sel_hi:[1,0]
	ds_read_b128 v[36:39], v20 offset:7168
	v_pk_fma_f32 v[22:23], v[4:5], v[60:61], v[22:23] op_sel:[0,1,0] op_sel_hi:[1,1,1]
	v_pk_mul_f32 v[84:85], v[4:5], v[52:53] op_sel:[0,1] op_sel_hi:[1,1]
	ds_read_b128 v[40:43], v20 offset:15360
	v_pk_fma_f32 v[22:23], v[6:7], v[62:63], v[22:23] op_sel:[0,0,0] op_sel_hi:[1,0,1]
	v_pk_fma_f32 v[28:29], v[6:7], v[54:55], v[28:29] op_sel:[0,0,0] op_sel_hi:[1,0,1]
	ds_read_b64 v[56:57], v21 offset:48128
	v_pk_fma_f32 v[22:23], v[8:9], v[62:63], v[22:23] op_sel:[0,1,0] op_sel_hi:[1,1,1]
	v_pk_fma_f32 v[84:85], v[8:9], v[54:55], v[84:85] op_sel:[0,1,0] op_sel_hi:[1,1,1]
	ds_read_b128 v[48:51], v20 offset:31744
	v_pk_add_f32 v[28:29], v[28:29], v[84:85]
	ds_read_b128 v[44:47], v20 offset:23552
	ds_read_b128 v[52:55], v20 offset:39936
	v_add_f32_dpp v24, v24, v24 row_ror:12 row_mask:0xf bank_mask:0x5
	v_add_f32_dpp v25, v25, v25 row_ror:4 row_mask:0xf bank_mask:0xa
	v_add_f32_dpp v22, v22, v22 quad_perm:[1,0,3,2] row_mask:0xf bank_mask:0xf
	v_add_f32_dpp v23, v23, v23 quad_perm:[1,0,3,2] row_mask:0xf bank_mask:0xf
	v_pk_mul_f32 v[84:85], v[2:3], v[64:65] op_sel:[0,0] op_sel_hi:[1,0]
	v_pk_mul_f32 v[86:87], v[4:5], v[64:65] op_sel:[0,1] op_sel_hi:[1,1]
	v_add_f32_dpp v26, v26, v26 row_ror:12 row_mask:0xf bank_mask:0x5
	v_add_f32_dpp v22, v22, v22 quad_perm:[2,3,0,1] row_mask:0xf bank_mask:0xf
	v_add_f32_dpp v23, v23, v23 quad_perm:[2,3,0,1] row_mask:0xf bank_mask:0xf
	v_pk_mul_f32 v[88:89], v[6:7], v[66:67] op_sel:[0,0] op_sel_hi:[1,0]
	v_pk_mul_f32 v[90:91], v[8:9], v[66:67] op_sel:[0,1] op_sel_hi:[1,1]
	v_add_f32_dpp v27, v27, v27 row_ror:4 row_mask:0xf bank_mask:0xa
	v_add_f32_dpp v22, v22, v22 row_half_mirror row_mask:0xf bank_mask:0xf
	v_add_f32_dpp v23, v23, v23 row_half_mirror row_mask:0xf bank_mask:0xf
	v_pk_fma_f32 v[84:85], v[72:73], v[80:81], v[84:85] op_sel:[0,0,0] op_sel_hi:[0,1,1]
	v_pk_fma_f32 v[86:87], v[72:73], v[80:81], v[86:87] op_sel:[1,0,0] op_sel_hi:[1,1,1]
	v_mov_b32_dpp v24, v25 quad_perm:[0,1,2,3] row_mask:0xf bank_mask:0xa
	v_add_f32_dpp v22, v22, v22 row_mirror row_mask:0xf bank_mask:0xf
	v_add_f32_dpp v23, v23, v23 row_mirror row_mask:0xf bank_mask:0xf
	v_pk_fma_f32 v[88:89], v[74:75], v[80:81], v[88:89] op_sel:[0,0,0] op_sel_hi:[0,1,1]
	v_pk_fma_f32 v[90:91], v[74:75], v[80:81], v[90:91] op_sel:[1,0,0] op_sel_hi:[1,1,1]
	v_mov_b32_dpp v26, v27 quad_perm:[0,1,2,3] row_mask:0xf bank_mask:0xa
	v_pk_fma_f32 v[2:3], v[68:69], v[22:23], v[84:85] op_sel:[0,0,0] op_sel_hi:[0,1,1] neg_lo:[1,0,0] neg_hi:[1,0,0]
	v_pk_fma_f32 v[4:5], v[68:69], v[22:23], v[86:87] op_sel:[1,0,0] op_sel_hi:[1,1,1] neg_lo:[1,0,0] neg_hi:[1,0,0]
	v_pk_fma_f32 v[6:7], v[70:71], v[22:23], v[88:89] op_sel:[0,0,0] op_sel_hi:[0,1,1] neg_lo:[1,0,0] neg_hi:[1,0,0]
	v_pk_fma_f32 v[8:9], v[70:71], v[22:23], v[90:91] op_sel:[1,0,0] op_sel_hi:[1,1,1] neg_lo:[1,0,0] neg_hi:[1,0,0]
	s_waitcnt lgkmcnt(0)
	v_pk_mul_f32 v[22:23], v[2:3], v[36:37] op_sel:[0,0] op_sel_hi:[1,0]
	v_pk_mul_f32 v[58:59], v[2:3], v[76:77] op_sel:[0,0] op_sel_hi:[1,0]
	ds_read_b128 v[60:63], v20 offset:7424
	v_pk_fma_f32 v[22:23], v[4:5], v[36:37], v[22:23] op_sel:[0,1,0] op_sel_hi:[1,1,1]
	v_pk_mul_f32 v[84:85], v[4:5], v[76:77] op_sel:[0,1] op_sel_hi:[1,1]
	ds_read_b128 v[64:67], v20 offset:15616
	v_pk_fma_f32 v[22:23], v[6:7], v[38:39], v[22:23] op_sel:[0,0,0] op_sel_hi:[1,0,1]
	v_pk_fma_f32 v[58:59], v[6:7], v[78:79], v[58:59] op_sel:[0,0,0] op_sel_hi:[1,0,1]
	ds_read_b64 v[80:81], v21 offset:48384
	v_pk_fma_f32 v[22:23], v[8:9], v[38:39], v[22:23] op_sel:[0,1,0] op_sel_hi:[1,1,1]
	v_pk_fma_f32 v[84:85], v[8:9], v[78:79], v[84:85] op_sel:[0,1,0] op_sel_hi:[1,1,1]
	ds_read_b128 v[72:75], v20 offset:32000
	v_pk_add_f32 v[58:59], v[58:59], v[84:85]
	ds_read_b128 v[68:71], v20 offset:23808
	ds_read_b128 v[76:79], v20 offset:40192
	v_add_f32_dpp v24, v24, v24 row_ror:8 row_mask:0xf bank_mask:0x3
	v_add_f32_dpp v26, v26, v26 row_ror:8 row_mask:0xf bank_mask:0xc
	v_add_f32_dpp v22, v22, v22 quad_perm:[1,0,3,2] row_mask:0xf bank_mask:0xf
	v_add_f32_dpp v23, v23, v23 quad_perm:[1,0,3,2] row_mask:0xf bank_mask:0xf
	v_pk_mul_f32 v[84:85], v[2:3], v[40:41] op_sel:[0,0] op_sel_hi:[1,0]
	v_pk_mul_f32 v[86:87], v[4:5], v[40:41] op_sel:[0,1] op_sel_hi:[1,1]
	v_mov_b32_dpp v24, v26 quad_perm:[0,1,2,3] row_mask:0xf bank_mask:0xc
	v_add_f32_dpp v22, v22, v22 quad_perm:[2,3,0,1] row_mask:0xf bank_mask:0xf
	v_add_f32_dpp v23, v23, v23 quad_perm:[2,3,0,1] row_mask:0xf bank_mask:0xf
	v_pk_mul_f32 v[88:89], v[6:7], v[42:43] op_sel:[0,0] op_sel_hi:[1,0]
	v_pk_mul_f32 v[90:91], v[8:9], v[42:43] op_sel:[0,1] op_sel_hi:[1,1]
	v_add_f32_dpp v24, v24, v24 quad_perm:[1,0,3,2] row_mask:0xf bank_mask:0xf
	v_add_f32_dpp v22, v22, v22 row_half_mirror row_mask:0xf bank_mask:0xf
	v_add_f32_dpp v23, v23, v23 row_half_mirror row_mask:0xf bank_mask:0xf
	v_pk_fma_f32 v[84:85], v[48:49], v[56:57], v[84:85] op_sel:[0,0,0] op_sel_hi:[0,1,1]
	v_pk_fma_f32 v[86:87], v[48:49], v[56:57], v[86:87] op_sel:[1,0,0] op_sel_hi:[1,1,1]
	v_add_f32_dpp v24, v24, v24 quad_perm:[2,3,0,1] row_mask:0xf bank_mask:0xf
	v_add_f32_dpp v22, v22, v22 row_mirror row_mask:0xf bank_mask:0xf
	v_add_f32_dpp v23, v23, v23 row_mirror row_mask:0xf bank_mask:0xf
	v_pk_fma_f32 v[88:89], v[50:51], v[56:57], v[88:89] op_sel:[0,0,0] op_sel_hi:[0,1,1]
	v_pk_fma_f32 v[90:91], v[50:51], v[56:57], v[90:91] op_sel:[1,0,0] op_sel_hi:[1,1,1]
	v_cndmask_b32_e64 v33, 0, v24, s[0:1]
	v_pk_fma_f32 v[2:3], v[44:45], v[22:23], v[84:85] op_sel:[0,0,0] op_sel_hi:[0,1,1] neg_lo:[1,0,0] neg_hi:[1,0,0]
	v_pk_fma_f32 v[4:5], v[44:45], v[22:23], v[86:87] op_sel:[1,0,0] op_sel_hi:[1,1,1] neg_lo:[1,0,0] neg_hi:[1,0,0]
	v_pk_fma_f32 v[6:7], v[46:47], v[22:23], v[88:89] op_sel:[0,0,0] op_sel_hi:[0,1,1] neg_lo:[1,0,0] neg_hi:[1,0,0]
	v_pk_fma_f32 v[8:9], v[46:47], v[22:23], v[90:91] op_sel:[1,0,0] op_sel_hi:[1,1,1] neg_lo:[1,0,0] neg_hi:[1,0,0]
	s_waitcnt lgkmcnt(0)
	v_pk_mul_f32 v[22:23], v[2:3], v[60:61] op_sel:[0,0] op_sel_hi:[1,0]
	v_pk_mul_f32 v[24:25], v[2:3], v[52:53] op_sel:[0,0] op_sel_hi:[1,0]
	ds_read_b128 v[36:39], v20 offset:7680
	v_pk_fma_f32 v[22:23], v[4:5], v[60:61], v[22:23] op_sel:[0,1,0] op_sel_hi:[1,1,1]
	v_pk_mul_f32 v[84:85], v[4:5], v[52:53] op_sel:[0,1] op_sel_hi:[1,1]
	ds_read_b128 v[40:43], v20 offset:15872
	v_pk_fma_f32 v[22:23], v[6:7], v[62:63], v[22:23] op_sel:[0,0,0] op_sel_hi:[1,0,1]
	v_pk_fma_f32 v[24:25], v[6:7], v[54:55], v[24:25] op_sel:[0,0,0] op_sel_hi:[1,0,1]
	ds_read_b64 v[56:57], v21 offset:48640
	v_pk_fma_f32 v[22:23], v[8:9], v[62:63], v[22:23] op_sel:[0,1,0] op_sel_hi:[1,1,1]
	v_pk_fma_f32 v[84:85], v[8:9], v[54:55], v[84:85] op_sel:[0,1,0] op_sel_hi:[1,1,1]
	ds_read_b128 v[48:51], v20 offset:32256
	v_pk_add_f32 v[24:25], v[24:25], v[84:85]
	ds_read_b128 v[44:47], v20 offset:24064
	ds_read_b128 v[52:55], v20 offset:40448
	v_add_f32_dpp v28, v28, v28 row_ror:12 row_mask:0xf bank_mask:0x5
	v_add_f32_dpp v29, v29, v29 row_ror:4 row_mask:0xf bank_mask:0xa
	v_add_f32_dpp v22, v22, v22 quad_perm:[1,0,3,2] row_mask:0xf bank_mask:0xf
	v_add_f32_dpp v23, v23, v23 quad_perm:[1,0,3,2] row_mask:0xf bank_mask:0xf
	v_pk_mul_f32 v[84:85], v[2:3], v[64:65] op_sel:[0,0] op_sel_hi:[1,0]
	v_pk_mul_f32 v[86:87], v[4:5], v[64:65] op_sel:[0,1] op_sel_hi:[1,1]
	v_add_f32_dpp v58, v58, v58 row_ror:12 row_mask:0xf bank_mask:0x5
	v_add_f32_dpp v22, v22, v22 quad_perm:[2,3,0,1] row_mask:0xf bank_mask:0xf
	v_add_f32_dpp v23, v23, v23 quad_perm:[2,3,0,1] row_mask:0xf bank_mask:0xf
	v_pk_mul_f32 v[88:89], v[6:7], v[66:67] op_sel:[0,0] op_sel_hi:[1,0]
	v_pk_mul_f32 v[90:91], v[8:9], v[66:67] op_sel:[0,1] op_sel_hi:[1,1]
	v_add_f32_dpp v59, v59, v59 row_ror:4 row_mask:0xf bank_mask:0xa
	v_add_f32_dpp v22, v22, v22 row_half_mirror row_mask:0xf bank_mask:0xf
	v_add_f32_dpp v23, v23, v23 row_half_mirror row_mask:0xf bank_mask:0xf
	v_pk_fma_f32 v[84:85], v[72:73], v[80:81], v[84:85] op_sel:[0,0,0] op_sel_hi:[0,1,1]
	v_pk_fma_f32 v[86:87], v[72:73], v[80:81], v[86:87] op_sel:[1,0,0] op_sel_hi:[1,1,1]
	v_mov_b32_dpp v28, v29 quad_perm:[0,1,2,3] row_mask:0xf bank_mask:0xa
	v_add_f32_dpp v22, v22, v22 row_mirror row_mask:0xf bank_mask:0xf
	v_add_f32_dpp v23, v23, v23 row_mirror row_mask:0xf bank_mask:0xf
	v_pk_fma_f32 v[88:89], v[74:75], v[80:81], v[88:89] op_sel:[0,0,0] op_sel_hi:[0,1,1]
	v_pk_fma_f32 v[90:91], v[74:75], v[80:81], v[90:91] op_sel:[1,0,0] op_sel_hi:[1,1,1]
	v_mov_b32_dpp v58, v59 quad_perm:[0,1,2,3] row_mask:0xf bank_mask:0xa
	v_pk_fma_f32 v[2:3], v[68:69], v[22:23], v[84:85] op_sel:[0,0,0] op_sel_hi:[0,1,1] neg_lo:[1,0,0] neg_hi:[1,0,0]
	v_pk_fma_f32 v[4:5], v[68:69], v[22:23], v[86:87] op_sel:[1,0,0] op_sel_hi:[1,1,1] neg_lo:[1,0,0] neg_hi:[1,0,0]
	v_pk_fma_f32 v[6:7], v[70:71], v[22:23], v[88:89] op_sel:[0,0,0] op_sel_hi:[0,1,1] neg_lo:[1,0,0] neg_hi:[1,0,0]
	v_pk_fma_f32 v[8:9], v[70:71], v[22:23], v[90:91] op_sel:[1,0,0] op_sel_hi:[1,1,1] neg_lo:[1,0,0] neg_hi:[1,0,0]
	s_waitcnt lgkmcnt(0)
	v_pk_mul_f32 v[22:23], v[2:3], v[36:37] op_sel:[0,0] op_sel_hi:[1,0]
	v_pk_mul_f32 v[26:27], v[2:3], v[76:77] op_sel:[0,0] op_sel_hi:[1,0]
	ds_read_b128 v[60:63], v20 offset:7936
	v_pk_fma_f32 v[22:23], v[4:5], v[36:37], v[22:23] op_sel:[0,1,0] op_sel_hi:[1,1,1]
	v_pk_mul_f32 v[84:85], v[4:5], v[76:77] op_sel:[0,1] op_sel_hi:[1,1]
	ds_read_b128 v[64:67], v20 offset:16128
	v_pk_fma_f32 v[22:23], v[6:7], v[38:39], v[22:23] op_sel:[0,0,0] op_sel_hi:[1,0,1]
	v_pk_fma_f32 v[26:27], v[6:7], v[78:79], v[26:27] op_sel:[0,0,0] op_sel_hi:[1,0,1]
	ds_read_b64 v[80:81], v21 offset:48896
	v_pk_fma_f32 v[22:23], v[8:9], v[38:39], v[22:23] op_sel:[0,1,0] op_sel_hi:[1,1,1]
	v_pk_fma_f32 v[84:85], v[8:9], v[78:79], v[84:85] op_sel:[0,1,0] op_sel_hi:[1,1,1]
	ds_read_b128 v[72:75], v20 offset:32512
	v_pk_add_f32 v[26:27], v[26:27], v[84:85]
	ds_read_b128 v[68:71], v20 offset:24320
	ds_read_b128 v[76:79], v20 offset:40704
	v_add_f32_dpp v28, v28, v28 row_ror:8 row_mask:0xf bank_mask:0x3
	v_add_f32_dpp v58, v58, v58 row_ror:8 row_mask:0xf bank_mask:0xc
	v_add_f32_dpp v22, v22, v22 quad_perm:[1,0,3,2] row_mask:0xf bank_mask:0xf
	v_add_f32_dpp v23, v23, v23 quad_perm:[1,0,3,2] row_mask:0xf bank_mask:0xf
	v_pk_mul_f32 v[84:85], v[2:3], v[40:41] op_sel:[0,0] op_sel_hi:[1,0]
	v_pk_mul_f32 v[86:87], v[4:5], v[40:41] op_sel:[0,1] op_sel_hi:[1,1]
	v_mov_b32_dpp v28, v58 quad_perm:[0,1,2,3] row_mask:0xf bank_mask:0xc
	v_add_f32_dpp v22, v22, v22 quad_perm:[2,3,0,1] row_mask:0xf bank_mask:0xf
	v_add_f32_dpp v23, v23, v23 quad_perm:[2,3,0,1] row_mask:0xf bank_mask:0xf
	v_pk_mul_f32 v[88:89], v[6:7], v[42:43] op_sel:[0,0] op_sel_hi:[1,0]
	v_pk_mul_f32 v[90:91], v[8:9], v[42:43] op_sel:[0,1] op_sel_hi:[1,1]
	v_add_f32_dpp v28, v28, v28 quad_perm:[1,0,3,2] row_mask:0xf bank_mask:0xf
	v_add_f32_dpp v22, v22, v22 row_half_mirror row_mask:0xf bank_mask:0xf
	v_add_f32_dpp v23, v23, v23 row_half_mirror row_mask:0xf bank_mask:0xf
	v_pk_fma_f32 v[84:85], v[48:49], v[56:57], v[84:85] op_sel:[0,0,0] op_sel_hi:[0,1,1]
	v_pk_fma_f32 v[86:87], v[48:49], v[56:57], v[86:87] op_sel:[1,0,0] op_sel_hi:[1,1,1]
	v_add_f32_dpp v28, v28, v28 quad_perm:[2,3,0,1] row_mask:0xf bank_mask:0xf
	v_add_f32_dpp v22, v22, v22 row_mirror row_mask:0xf bank_mask:0xf
	v_add_f32_dpp v23, v23, v23 row_mirror row_mask:0xf bank_mask:0xf
	v_pk_fma_f32 v[88:89], v[50:51], v[56:57], v[88:89] op_sel:[0,0,0] op_sel_hi:[0,1,1]
	v_pk_fma_f32 v[90:91], v[50:51], v[56:57], v[90:91] op_sel:[1,0,0] op_sel_hi:[1,1,1]
	v_cndmask_b32_e64 v33, v33, v28, s[6:7]
	v_pk_fma_f32 v[2:3], v[44:45], v[22:23], v[84:85] op_sel:[0,0,0] op_sel_hi:[0,1,1] neg_lo:[1,0,0] neg_hi:[1,0,0]
	v_pk_fma_f32 v[4:5], v[44:45], v[22:23], v[86:87] op_sel:[1,0,0] op_sel_hi:[1,1,1] neg_lo:[1,0,0] neg_hi:[1,0,0]
	v_pk_fma_f32 v[6:7], v[46:47], v[22:23], v[88:89] op_sel:[0,0,0] op_sel_hi:[0,1,1] neg_lo:[1,0,0] neg_hi:[1,0,0]
	v_pk_fma_f32 v[8:9], v[46:47], v[22:23], v[90:91] op_sel:[1,0,0] op_sel_hi:[1,1,1] neg_lo:[1,0,0] neg_hi:[1,0,0]
	s_waitcnt lgkmcnt(0)
	v_pk_mul_f32 v[22:23], v[2:3], v[60:61] op_sel:[0,0] op_sel_hi:[1,0]
	v_pk_mul_f32 v[28:29], v[2:3], v[52:53] op_sel:[0,0] op_sel_hi:[1,0]
	v_pk_fma_f32 v[22:23], v[4:5], v[60:61], v[22:23] op_sel:[0,1,0] op_sel_hi:[1,1,1]
	v_pk_mul_f32 v[84:85], v[4:5], v[52:53] op_sel:[0,1] op_sel_hi:[1,1]
	v_pk_fma_f32 v[22:23], v[6:7], v[62:63], v[22:23] op_sel:[0,0,0] op_sel_hi:[1,0,1]
	v_pk_fma_f32 v[28:29], v[6:7], v[54:55], v[28:29] op_sel:[0,0,0] op_sel_hi:[1,0,1]
	v_pk_fma_f32 v[22:23], v[8:9], v[62:63], v[22:23] op_sel:[0,1,0] op_sel_hi:[1,1,1]
	v_pk_fma_f32 v[84:85], v[8:9], v[54:55], v[84:85] op_sel:[0,1,0] op_sel_hi:[1,1,1]
	v_pk_add_f32 v[28:29], v[28:29], v[84:85]
	v_add_f32_dpp v24, v24, v24 row_ror:12 row_mask:0xf bank_mask:0x5
	v_add_f32_dpp v25, v25, v25 row_ror:4 row_mask:0xf bank_mask:0xa
	v_add_f32_dpp v22, v22, v22 quad_perm:[1,0,3,2] row_mask:0xf bank_mask:0xf
	v_add_f32_dpp v23, v23, v23 quad_perm:[1,0,3,2] row_mask:0xf bank_mask:0xf
	v_pk_mul_f32 v[84:85], v[2:3], v[64:65] op_sel:[0,0] op_sel_hi:[1,0]
	v_pk_mul_f32 v[86:87], v[4:5], v[64:65] op_sel:[0,1] op_sel_hi:[1,1]
	v_add_f32_dpp v26, v26, v26 row_ror:12 row_mask:0xf bank_mask:0x5
	v_add_f32_dpp v22, v22, v22 quad_perm:[2,3,0,1] row_mask:0xf bank_mask:0xf
	v_add_f32_dpp v23, v23, v23 quad_perm:[2,3,0,1] row_mask:0xf bank_mask:0xf
	v_pk_mul_f32 v[88:89], v[6:7], v[66:67] op_sel:[0,0] op_sel_hi:[1,0]
	v_pk_mul_f32 v[90:91], v[8:9], v[66:67] op_sel:[0,1] op_sel_hi:[1,1]
	v_add_f32_dpp v27, v27, v27 row_ror:4 row_mask:0xf bank_mask:0xa
	v_add_f32_dpp v22, v22, v22 row_half_mirror row_mask:0xf bank_mask:0xf
	v_add_f32_dpp v23, v23, v23 row_half_mirror row_mask:0xf bank_mask:0xf
	v_pk_fma_f32 v[84:85], v[72:73], v[80:81], v[84:85] op_sel:[0,0,0] op_sel_hi:[0,1,1]
	v_pk_fma_f32 v[86:87], v[72:73], v[80:81], v[86:87] op_sel:[1,0,0] op_sel_hi:[1,1,1]
	v_mov_b32_dpp v24, v25 quad_perm:[0,1,2,3] row_mask:0xf bank_mask:0xa
	v_add_f32_dpp v22, v22, v22 row_mirror row_mask:0xf bank_mask:0xf
	v_add_f32_dpp v23, v23, v23 row_mirror row_mask:0xf bank_mask:0xf
	v_pk_fma_f32 v[88:89], v[74:75], v[80:81], v[88:89] op_sel:[0,0,0] op_sel_hi:[0,1,1]
	v_pk_fma_f32 v[90:91], v[74:75], v[80:81], v[90:91] op_sel:[1,0,0] op_sel_hi:[1,1,1]
	v_mov_b32_dpp v26, v27 quad_perm:[0,1,2,3] row_mask:0xf bank_mask:0xa
	v_pk_fma_f32 v[2:3], v[68:69], v[22:23], v[84:85] op_sel:[0,0,0] op_sel_hi:[0,1,1] neg_lo:[1,0,0] neg_hi:[1,0,0]
	v_pk_fma_f32 v[4:5], v[68:69], v[22:23], v[86:87] op_sel:[1,0,0] op_sel_hi:[1,1,1] neg_lo:[1,0,0] neg_hi:[1,0,0]
	v_pk_fma_f32 v[6:7], v[70:71], v[22:23], v[88:89] op_sel:[0,0,0] op_sel_hi:[0,1,1] neg_lo:[1,0,0] neg_hi:[1,0,0]
	v_pk_fma_f32 v[8:9], v[70:71], v[22:23], v[90:91] op_sel:[1,0,0] op_sel_hi:[1,1,1] neg_lo:[1,0,0] neg_hi:[1,0,0]
	s_waitcnt lgkmcnt(0)
	v_pk_mul_f32 v[58:59], v[2:3], v[76:77] op_sel:[0,0] op_sel_hi:[1,0]
	v_pk_mul_f32 v[84:85], v[4:5], v[76:77] op_sel:[0,1] op_sel_hi:[1,1]
	v_pk_fma_f32 v[58:59], v[6:7], v[78:79], v[58:59] op_sel:[0,0,0] op_sel_hi:[1,0,1]
	v_pk_fma_f32 v[84:85], v[8:9], v[78:79], v[84:85] op_sel:[0,1,0] op_sel_hi:[1,1,1]
	v_pk_add_f32 v[58:59], v[58:59], v[84:85]
	v_add_f32_dpp v24, v24, v24 row_ror:8 row_mask:0xf bank_mask:0x3
	v_add_f32_dpp v26, v26, v26 row_ror:8 row_mask:0xf bank_mask:0xc
	s_nop 1
	v_mov_b32_dpp v24, v26 quad_perm:[0,1,2,3] row_mask:0xf bank_mask:0xc
	s_nop 1
	v_add_f32_dpp v24, v24, v24 quad_perm:[1,0,3,2] row_mask:0xf bank_mask:0xf
	s_nop 1
	v_add_f32_dpp v24, v24, v24 quad_perm:[2,3,0,1] row_mask:0xf bank_mask:0xf
	v_cndmask_b32_e64 v33, v33, v24, s[8:9]
	v_add_f32_dpp v28, v28, v28 row_ror:12 row_mask:0xf bank_mask:0x5
	v_add_f32_dpp v29, v29, v29 row_ror:4 row_mask:0xf bank_mask:0xa
	v_add_f32_dpp v58, v58, v58 row_ror:12 row_mask:0xf bank_mask:0x5
	v_add_f32_dpp v59, v59, v59 row_ror:4 row_mask:0xf bank_mask:0xa
	v_mov_b32_dpp v28, v29 quad_perm:[0,1,2,3] row_mask:0xf bank_mask:0xa
	s_nop 0
	v_mov_b32_dpp v58, v59 quad_perm:[0,1,2,3] row_mask:0xf bank_mask:0xa
	v_add_f32_dpp v28, v28, v28 row_ror:8 row_mask:0xf bank_mask:0x3
	s_nop 0
	v_add_f32_dpp v58, v58, v58 row_ror:8 row_mask:0xf bank_mask:0xc
	s_nop 1
	v_mov_b32_dpp v28, v58 quad_perm:[0,1,2,3] row_mask:0xf bank_mask:0xc
	s_nop 1
	v_add_f32_dpp v28, v28, v28 quad_perm:[1,0,3,2] row_mask:0xf bank_mask:0xf
	s_nop 1
	v_add_f32_dpp v28, v28, v28 quad_perm:[2,3,0,1] row_mask:0xf bank_mask:0xf
	v_cndmask_b32_e64 v33, v33, v28, s[10:11]
	v_lshl_add_u32 v35, s23, 12, v11
	s_add_i32 s22, s22, 1
	ds_write2st64_b32 v35, v30, v31 offset1:4
	ds_write2st64_b32 v35, v32, v33 offset0:8 offset1:12
	s_cmp_eq_u32 s22, 64
	s_waitcnt lgkmcnt(0)
	s_barrier
	s_cbranch_scc0 .LBB0_1750
	s_setprio 0
	s_lshl_b32 s0, s18, 4
	s_or_b32 s0, s0, s26
	s_ashr_i32 s1, s0, 31
	s_lshl_b64 s[0:1], s[0:1], 6
	s_lshl_b32 s2, s27, 5
	s_or_b32 s0, s0, s2
	v_or_b32_e32 v12, s0, v1
	v_mov_b32_e32 v13, s1
	v_lshlrev_b64 v[12:13], 8, v[12:13]
	v_lshl_add_u64 v[12:13], s[82:83], 0, v[12:13]
	v_mov_b32_e32 v11, 0
	v_lshl_add_u64 v[10:11], v[12:13], 0, v[10:11]
	s_mov_b64 s[0:1], 0x4100000
	v_lshl_add_u64 v[12:13], v[10:11], 0, s[0:1]
	v_add_co_u32_e32 v10, vcc, 0x4100000, v10
	s_nop 1
	v_addc_co_u32_e32 v11, vcc, 0, v11, vcc
	v_mov_b32_e32 v14, v2
	v_mov_b32_e32 v15, v4
	v_mov_b32_e32 v16, v6
	v_mov_b32_e32 v17, v8
	v_mov_b32_e32 v18, v3
	v_mov_b32_e32 v19, v5
	v_mov_b32_e32 v20, v7
	v_mov_b32_e32 v21, v9
	global_store_dwordx4 v[10:11], v[14:17], off
	global_store_dwordx4 v[12:13], v[18:21], off offset:256
